# early barrier k=8 with the next load segment's free-register ds_reads hoisted into the tail (all SP2 loops), P1a k=4, int8 nop trims
# baseline (speedup 1.0000x reference)
.LBB0_412:
	ds_read_b128 v[130:133], v191
	ds_read_b128 v[134:137], v191 offset:1024
	ds_read_b128 v[138:141], v191 offset:2048
	ds_read_b128 v[142:145], v191 offset:3072
	ds_read_b128 v[146:149], v192
	ds_read_b128 v[150:153], v192 offset:1024
	ds_read_b128 v[174:177], v192 offset:2048
	s_waitcnt lgkmcnt(0)
	ds_read_b128 v[178:181], v192 offset:3072
	s_add_u32 s42, s40, 0xfff00080
	s_addc_u32 s43, s41, -1
	s_cmp_eq_u32 s29, 60
	s_cselect_b32 s45, s0, s43
	s_cselect_b32 s44, s1, s42
	s_cselect_b32 s43, s7, s27
	s_cselect_b32 s42, s14, s15
	v_lshl_add_u64 v[186:187], s[40:41], 0, v[170:171]
	s_add_i32 m0, s9, 0xc000
	ds_read_b128 v[182:185], v193
	ds_read_b128 v[204:207], v193 offset:1024
	ds_read_b128 v[208:211], v193 offset:2048
	ds_read_b128 v[212:215], v193 offset:3072
	ds_read_b128 v[216:219], v193 offset:4096
	ds_read_b128 v[220:223], v193 offset:5120
	ds_read_b128 v[224:227], v193 offset:6144
	ds_read_b128 v[234:237], v193 offset:7168
	global_load_lds_dwordx4 v[186:187], off
	v_lshl_add_u64 v[186:187], s[40:41], 0, v[172:173]
	s_add_i32 m0, s9, 0xe000
	s_nop 0
	global_load_lds_dwordx4 v[186:187], off
	s_waitcnt vmcnt(8)
	s_waitcnt lgkmcnt(0)
	s_barrier
	s_setprio 1
	s_waitcnt lgkmcnt(0)
	v_mfma_f32_16x16x32_bf16 v[126:129], v[130:133], v[182:185], v[126:129]
	v_mfma_f32_16x16x32_bf16 v[122:125], v[138:141], v[182:185], v[122:125]
	v_mfma_f32_16x16x32_bf16 v[118:121], v[130:133], v[208:211], v[118:121]
	v_mfma_f32_16x16x32_bf16 v[110:113], v[138:141], v[208:211], v[110:113]
	v_mfma_f32_16x16x32_bf16 v[102:105], v[130:133], v[216:219], v[102:105]
	v_mfma_f32_16x16x32_bf16 v[94:97], v[138:141], v[216:219], v[94:97]
	v_mfma_f32_16x16x32_bf16 v[86:89], v[130:133], v[224:227], v[86:89]
	v_mfma_f32_16x16x32_bf16 v[78:81], v[138:141], v[224:227], v[78:81]
	v_mfma_f32_16x16x32_bf16 v[126:129], v[134:137], v[204:207], v[126:129]
	v_mfma_f32_16x16x32_bf16 v[122:125], v[142:145], v[204:207], v[122:125]
	v_mfma_f32_16x16x32_bf16 v[118:121], v[134:137], v[212:215], v[118:121]
	v_mfma_f32_16x16x32_bf16 v[110:113], v[142:145], v[212:215], v[110:113]
	v_mfma_f32_16x16x32_bf16 v[102:105], v[134:137], v[220:223], v[102:105]
	v_mfma_f32_16x16x32_bf16 v[94:97], v[142:145], v[220:223], v[94:97]
	v_mfma_f32_16x16x32_bf16 v[86:89], v[134:137], v[234:237], v[86:89]
	v_mfma_f32_16x16x32_bf16 v[78:81], v[142:145], v[234:237], v[78:81]
	v_mfma_f32_16x16x32_bf16 v[114:117], v[146:149], v[182:185], v[114:117]
	v_mfma_f32_16x16x32_bf16 v[106:109], v[174:177], v[182:185], v[106:109]
	v_mfma_f32_16x16x32_bf16 v[98:101], v[146:149], v[208:211], v[98:101]
	v_mfma_f32_16x16x32_bf16 v[90:93], v[174:177], v[208:211], v[90:93]
	v_mfma_f32_16x16x32_bf16 v[82:85], v[146:149], v[216:219], v[82:85]
	v_mfma_f32_16x16x32_bf16 v[74:77], v[174:177], v[216:219], v[74:77]
	v_mfma_f32_16x16x32_bf16 v[70:73], v[146:149], v[224:227], v[70:73]
	v_mfma_f32_16x16x32_bf16 v[66:69], v[174:177], v[224:227], v[66:69]
	s_barrier
	s_setprio 2
	v_mfma_f32_16x16x32_bf16 v[114:117], v[150:153], v[204:207], v[114:117]
	ds_read_b128 v[182:185], v193 offset:16384
	v_mfma_f32_16x16x32_bf16 v[106:109], v[178:181], v[204:207], v[106:109]
	v_mfma_f32_16x16x32_bf16 v[98:101], v[150:153], v[212:215], v[98:101]
	v_mfma_f32_16x16x32_bf16 v[90:93], v[178:181], v[212:215], v[90:93]
	ds_read_b128 v[204:207], v193 offset:17408
	ds_read_b128 v[208:211], v193 offset:18432
	v_mfma_f32_16x16x32_bf16 v[82:85], v[150:153], v[220:223], v[82:85]
	v_mfma_f32_16x16x32_bf16 v[74:77], v[178:181], v[220:223], v[74:77]
	ds_read_b128 v[212:215], v193 offset:19456
	ds_read_b128 v[216:219], v193 offset:20480
	v_mfma_f32_16x16x32_bf16 v[70:73], v[150:153], v[234:237], v[70:73]
	v_mfma_f32_16x16x32_bf16 v[66:69], v[178:181], v[234:237], v[66:69]
	ds_read_b128 v[220:223], v193 offset:21504
	ds_read_b128 v[224:227], v193 offset:22528
	s_setprio 0
	s_add_i32 s46, s52, s8
	v_lshl_add_u64 v[186:187], s[42:43], 0, v[158:159]
	s_mov_b32 m0, s46
	ds_read_b128 v[234:237], v193 offset:23552
	global_load_lds_dwordx4 v[186:187], off
	s_add_i32 m0, s46, 0x2000
	s_add_u32 s46, s42, 0x100000
	v_lshl_add_u64 v[194:195], s[42:43], 0, v[162:163]
	s_addc_u32 s47, s43, 0
	s_add_i32 s56, s53, s8
	global_load_lds_dwordx4 v[194:195], off
	v_lshl_add_u64 v[200:201], s[46:47], 0, v[158:159]
	s_mov_b32 m0, s56
	v_lshl_add_u64 v[238:239], s[44:45], 0, v[160:161]
	global_load_lds_dwordx4 v[200:201], off
	v_lshl_add_u64 v[200:201], s[46:47], 0, v[162:163]
	s_add_i32 m0, s56, 0x2000
	s_nop 0
	global_load_lds_dwordx4 v[200:201], off
	v_lshl_add_u64 v[200:201], s[44:45], 0, v[156:157]
	s_mov_b32 m0, s9
	s_nop 0
	global_load_lds_dwordx4 v[200:201], off
	s_mov_b32 m0, s13
	s_nop 0
	global_load_lds_dwordx4 v[238:239], off
	s_waitcnt vmcnt(8)
	s_waitcnt lgkmcnt(0)
	s_barrier
	s_setprio 1
	s_waitcnt lgkmcnt(0)
	v_mfma_f32_16x16x32_bf16 v[62:65], v[130:133], v[182:185], v[62:65]
	v_mfma_f32_16x16x32_bf16 v[58:61], v[138:141], v[182:185], v[58:61]
	v_mfma_f32_16x16x32_bf16 v[54:57], v[130:133], v[208:211], v[54:57]
	v_mfma_f32_16x16x32_bf16 v[46:49], v[138:141], v[208:211], v[46:49]
	v_mfma_f32_16x16x32_bf16 v[38:41], v[130:133], v[216:219], v[38:41]
	v_mfma_f32_16x16x32_bf16 v[30:33], v[138:141], v[216:219], v[30:33]
	v_mfma_f32_16x16x32_bf16 v[22:25], v[130:133], v[224:227], v[22:25]
	v_mfma_f32_16x16x32_bf16 v[14:17], v[138:141], v[224:227], v[14:17]
	v_mfma_f32_16x16x32_bf16 v[62:65], v[134:137], v[204:207], v[62:65]
	v_mfma_f32_16x16x32_bf16 v[58:61], v[142:145], v[204:207], v[58:61]
	v_mfma_f32_16x16x32_bf16 v[54:57], v[134:137], v[212:215], v[54:57]
	v_mfma_f32_16x16x32_bf16 v[46:49], v[142:145], v[212:215], v[46:49]
	v_mfma_f32_16x16x32_bf16 v[38:41], v[134:137], v[220:223], v[38:41]
	v_mfma_f32_16x16x32_bf16 v[30:33], v[142:145], v[220:223], v[30:33]
	v_mfma_f32_16x16x32_bf16 v[22:25], v[134:137], v[234:237], v[22:25]
	v_mfma_f32_16x16x32_bf16 v[14:17], v[142:145], v[234:237], v[14:17]
	v_mfma_f32_16x16x32_bf16 v[50:53], v[146:149], v[182:185], v[50:53]
	v_mfma_f32_16x16x32_bf16 v[42:45], v[174:177], v[182:185], v[42:45]
	v_mfma_f32_16x16x32_bf16 v[34:37], v[146:149], v[208:211], v[34:37]
	v_mfma_f32_16x16x32_bf16 v[26:29], v[174:177], v[208:211], v[26:29]
	v_mfma_f32_16x16x32_bf16 v[18:21], v[146:149], v[216:219], v[18:21]
	v_mfma_f32_16x16x32_bf16 v[10:13], v[174:177], v[216:219], v[10:13]
	v_mfma_f32_16x16x32_bf16 v[6:9], v[146:149], v[224:227], v[6:9]
	v_mfma_f32_16x16x32_bf16 v[2:5], v[174:177], v[224:227], v[2:5]
	s_barrier
	s_setprio 2
	v_mfma_f32_16x16x32_bf16 v[50:53], v[150:153], v[204:207], v[50:53]
	v_mfma_f32_16x16x32_bf16 v[42:45], v[178:181], v[204:207], v[42:45]
	v_mfma_f32_16x16x32_bf16 v[34:37], v[150:153], v[212:215], v[34:37]
	v_mfma_f32_16x16x32_bf16 v[26:29], v[178:181], v[212:215], v[26:29]
	v_mfma_f32_16x16x32_bf16 v[18:21], v[150:153], v[220:223], v[18:21]
	v_mfma_f32_16x16x32_bf16 v[10:13], v[178:181], v[220:223], v[10:13]
	v_mfma_f32_16x16x32_bf16 v[6:9], v[150:153], v[234:237], v[6:9]
	v_mfma_f32_16x16x32_bf16 v[2:5], v[178:181], v[234:237], v[2:5]
	s_setprio 0
	s_add_i32 s46, 0, 0x18000
	s_add_i32 s47, 0, 0x1c000
	v_add_u32_e32 v142, s46, v188
	v_add_u32_e32 v164, s47, v188
	ds_read_b128 v[130:133], v142
	ds_read_b128 v[134:137], v142 offset:1024
	ds_read_b128 v[138:141], v142 offset:2048
	ds_read_b128 v[142:145], v142 offset:3072
	ds_read_b128 v[146:149], v164
	ds_read_b128 v[150:153], v164 offset:1024
	ds_read_b128 v[174:177], v164 offset:2048
	ds_read_b128 v[178:181], v164 offset:3072
	s_add_u32 s44, s44, 0x100000
	s_addc_u32 s45, s45, 0
	s_mov_b32 m0, s33
	v_lshl_add_u64 v[240:241], s[44:45], 0, v[156:157]
	ds_read_b128 v[182:185], v193 offset:32768
	ds_read_b128 v[204:207], v193 offset:33792
	ds_read_b128 v[208:211], v193 offset:34816
	ds_read_b128 v[212:215], v193 offset:35840
	ds_read_b128 v[216:219], v193 offset:36864
	ds_read_b128 v[220:223], v193 offset:37888
	ds_read_b128 v[224:227], v193 offset:38912
	ds_read_b128 v[234:237], v193 offset:39936
	global_load_lds_dwordx4 v[240:241], off
	v_lshl_add_u64 v[240:241], s[44:45], 0, v[160:161]
	s_mov_b32 m0, s39
	s_nop 0
	global_load_lds_dwordx4 v[240:241], off
	s_waitcnt vmcnt(8)
	s_waitcnt lgkmcnt(0)
	s_barrier
	s_setprio 1
	s_waitcnt lgkmcnt(0)
	v_mfma_f32_16x16x32_bf16 v[126:129], v[130:133], v[182:185], v[126:129]
	v_mfma_f32_16x16x32_bf16 v[122:125], v[138:141], v[182:185], v[122:125]
	v_mfma_f32_16x16x32_bf16 v[118:121], v[130:133], v[208:211], v[118:121]
	v_mfma_f32_16x16x32_bf16 v[110:113], v[138:141], v[208:211], v[110:113]
	v_mfma_f32_16x16x32_bf16 v[102:105], v[130:133], v[216:219], v[102:105]
	v_mfma_f32_16x16x32_bf16 v[94:97], v[138:141], v[216:219], v[94:97]
	v_mfma_f32_16x16x32_bf16 v[86:89], v[130:133], v[224:227], v[86:89]
	v_mfma_f32_16x16x32_bf16 v[78:81], v[138:141], v[224:227], v[78:81]
	v_mfma_f32_16x16x32_bf16 v[126:129], v[134:137], v[204:207], v[126:129]
	v_mfma_f32_16x16x32_bf16 v[122:125], v[142:145], v[204:207], v[122:125]
	v_mfma_f32_16x16x32_bf16 v[118:121], v[134:137], v[212:215], v[118:121]
	v_mfma_f32_16x16x32_bf16 v[110:113], v[142:145], v[212:215], v[110:113]
	v_mfma_f32_16x16x32_bf16 v[102:105], v[134:137], v[220:223], v[102:105]
	v_mfma_f32_16x16x32_bf16 v[94:97], v[142:145], v[220:223], v[94:97]
	v_mfma_f32_16x16x32_bf16 v[86:89], v[134:137], v[234:237], v[86:89]
	v_mfma_f32_16x16x32_bf16 v[78:81], v[142:145], v[234:237], v[78:81]
	v_mfma_f32_16x16x32_bf16 v[114:117], v[146:149], v[182:185], v[114:117]
	v_mfma_f32_16x16x32_bf16 v[106:109], v[174:177], v[182:185], v[106:109]
	v_mfma_f32_16x16x32_bf16 v[98:101], v[146:149], v[208:211], v[98:101]
	v_mfma_f32_16x16x32_bf16 v[90:93], v[174:177], v[208:211], v[90:93]
	v_mfma_f32_16x16x32_bf16 v[82:85], v[146:149], v[216:219], v[82:85]
	v_mfma_f32_16x16x32_bf16 v[74:77], v[174:177], v[216:219], v[74:77]
	v_mfma_f32_16x16x32_bf16 v[70:73], v[146:149], v[224:227], v[70:73]
	v_mfma_f32_16x16x32_bf16 v[66:69], v[174:177], v[224:227], v[66:69]
	s_barrier
	s_setprio 2
	v_mfma_f32_16x16x32_bf16 v[114:117], v[150:153], v[204:207], v[114:117]
	ds_read_b128 v[182:185], v193 offset:49152
	v_mfma_f32_16x16x32_bf16 v[106:109], v[178:181], v[204:207], v[106:109]
	v_mfma_f32_16x16x32_bf16 v[98:101], v[150:153], v[212:215], v[98:101]
	v_mfma_f32_16x16x32_bf16 v[90:93], v[178:181], v[212:215], v[90:93]
	ds_read_b128 v[204:207], v193 offset:50176
	ds_read_b128 v[208:211], v193 offset:51200
	v_mfma_f32_16x16x32_bf16 v[82:85], v[150:153], v[220:223], v[82:85]
	v_mfma_f32_16x16x32_bf16 v[74:77], v[178:181], v[220:223], v[74:77]
	ds_read_b128 v[212:215], v193 offset:52224
	ds_read_b128 v[216:219], v193 offset:53248
	v_mfma_f32_16x16x32_bf16 v[70:73], v[150:153], v[234:237], v[70:73]
	v_mfma_f32_16x16x32_bf16 v[66:69], v[178:181], v[234:237], v[66:69]
	ds_read_b128 v[220:223], v193 offset:54272
	ds_read_b128 v[224:227], v193 offset:55296
	s_setprio 0
	s_add_i32 s44, s46, s8
	v_lshl_add_u64 v[186:187], v[186:187], 0, s[20:21]
	s_mov_b32 m0, s44
	ds_read_b128 v[234:237], v193 offset:56320
	global_load_lds_dwordx4 v[186:187], off
	s_add_i32 m0, s44, 0x2000
	s_add_u32 s42, s42, 0x100080
	v_lshl_add_u64 v[186:187], v[194:195], 0, s[20:21]
	s_addc_u32 s43, s43, 0
	s_add_i32 s44, s47, s8
	global_load_lds_dwordx4 v[186:187], off
	v_lshl_add_u64 v[186:187], s[42:43], 0, v[158:159]
	s_mov_b32 m0, s44
	s_nop 0
	global_load_lds_dwordx4 v[186:187], off
	v_lshl_add_u64 v[186:187], s[42:43], 0, v[162:163]
	s_add_i32 m0, s44, 0x2000
	s_nop 0
	global_load_lds_dwordx4 v[186:187], off
	v_lshl_add_u64 v[186:187], v[200:201], 0, s[20:21]
	s_mov_b32 m0, s50
	s_nop 0
	global_load_lds_dwordx4 v[186:187], off
	v_lshl_add_u64 v[186:187], v[238:239], 0, s[20:21]
	s_mov_b32 m0, s51
	s_nop 0
	global_load_lds_dwordx4 v[186:187], off
	s_waitcnt vmcnt(8)
	s_waitcnt lgkmcnt(0)
	s_barrier
	s_setprio 1
	s_waitcnt lgkmcnt(0)
	v_mfma_f32_16x16x32_bf16 v[62:65], v[130:133], v[182:185], v[62:65]
	v_mfma_f32_16x16x32_bf16 v[58:61], v[138:141], v[182:185], v[58:61]
	v_mfma_f32_16x16x32_bf16 v[54:57], v[130:133], v[208:211], v[54:57]
	v_mfma_f32_16x16x32_bf16 v[46:49], v[138:141], v[208:211], v[46:49]
	v_mfma_f32_16x16x32_bf16 v[38:41], v[130:133], v[216:219], v[38:41]
	v_mfma_f32_16x16x32_bf16 v[30:33], v[138:141], v[216:219], v[30:33]
	v_mfma_f32_16x16x32_bf16 v[22:25], v[130:133], v[224:227], v[22:25]
	v_mfma_f32_16x16x32_bf16 v[14:17], v[138:141], v[224:227], v[14:17]
	v_mfma_f32_16x16x32_bf16 v[62:65], v[134:137], v[204:207], v[62:65]
	v_mfma_f32_16x16x32_bf16 v[58:61], v[142:145], v[204:207], v[58:61]
	v_mfma_f32_16x16x32_bf16 v[54:57], v[134:137], v[212:215], v[54:57]
	v_mfma_f32_16x16x32_bf16 v[46:49], v[142:145], v[212:215], v[46:49]
	v_mfma_f32_16x16x32_bf16 v[38:41], v[134:137], v[220:223], v[38:41]
	v_mfma_f32_16x16x32_bf16 v[30:33], v[142:145], v[220:223], v[30:33]
	v_mfma_f32_16x16x32_bf16 v[22:25], v[134:137], v[234:237], v[22:25]
	v_mfma_f32_16x16x32_bf16 v[14:17], v[142:145], v[234:237], v[14:17]
	v_mfma_f32_16x16x32_bf16 v[50:53], v[146:149], v[182:185], v[50:53]
	v_mfma_f32_16x16x32_bf16 v[42:45], v[174:177], v[182:185], v[42:45]
	v_mfma_f32_16x16x32_bf16 v[34:37], v[146:149], v[208:211], v[34:37]
	v_mfma_f32_16x16x32_bf16 v[26:29], v[174:177], v[208:211], v[26:29]
	v_mfma_f32_16x16x32_bf16 v[18:21], v[146:149], v[216:219], v[18:21]
	v_mfma_f32_16x16x32_bf16 v[10:13], v[174:177], v[216:219], v[10:13]
	v_mfma_f32_16x16x32_bf16 v[6:9], v[146:149], v[224:227], v[6:9]
	v_mfma_f32_16x16x32_bf16 v[2:5], v[174:177], v[224:227], v[2:5]
	v_mfma_f32_16x16x32_bf16 v[50:53], v[150:153], v[204:207], v[50:53]
	v_mfma_f32_16x16x32_bf16 v[42:45], v[178:181], v[204:207], v[42:45]
	v_mfma_f32_16x16x32_bf16 v[34:37], v[150:153], v[212:215], v[34:37]
	v_mfma_f32_16x16x32_bf16 v[26:29], v[178:181], v[212:215], v[26:29]
	s_barrier
	s_setprio 2
	v_mfma_f32_16x16x32_bf16 v[18:21], v[150:153], v[220:223], v[18:21]
	v_mfma_f32_16x16x32_bf16 v[10:13], v[178:181], v[220:223], v[10:13]
	v_mfma_f32_16x16x32_bf16 v[6:9], v[150:153], v[234:237], v[6:9]
	v_mfma_f32_16x16x32_bf16 v[2:5], v[178:181], v[234:237], v[2:5]
	s_setprio 0
	s_add_i32 s29, s29, 2
	s_add_u32 s40, s40, 0x100
	s_addc_u32 s41, s41, 0
	s_add_u32 s15, s15, 0x100
	s_addc_u32 s27, s27, 0
	s_cmp_gt_u32 s29, 61
	s_cbranch_scc0 .LBB0_412
	s_and_b64 vcc, exec, s[22:23]
	s_cbranch_vccz .LBB0_415
	s_barrier

.LBB0_514:
	ds_read_b128 v[156:159], v146
	ds_read_b128 v[160:163], v146 offset:1024
	ds_read_b128 v[164:167], v146 offset:2048
	ds_read_b128 v[168:171], v146 offset:3072
	ds_read_b128 v[172:175], v147
	s_waitcnt lgkmcnt(0)
	ds_read_b128 v[176:179], v147 offset:1024
	ds_read_b128 v[180:183], v147 offset:2048
	ds_read_b128 v[184:187], v147 offset:3072
	s_add_u32 s28, s26, 0xfff00080
	s_addc_u32 s29, s27, -1
	s_cmp_eq_u32 s50, 4
	s_cselect_b32 s31, s19, s29
	s_cselect_b32 s30, s18, s28
	s_cselect_b32 s29, s21, s49
	s_cselect_b32 s28, s20, s23
	s_mov_b32 m0, s36
	v_lshl_add_u64 v[142:143], s[26:27], 0, v[138:139]
	ds_read_b128 v[190:193], v148
	ds_read_b128 v[204:207], v148 offset:1024
	ds_read_b128 v[208:211], v148 offset:2048
	ds_read_b128 v[212:215], v148 offset:3072
	ds_read_b128 v[216:219], v148 offset:4096
	ds_read_b128 v[220:223], v148 offset:5120
	ds_read_b128 v[224:227], v148 offset:6144
	ds_read_b128 v[234:237], v148 offset:7168
	global_load_lds_dwordx4 v[142:143], off
	v_lshl_add_u64 v[142:143], s[26:27], 0, v[140:141]
	s_mov_b32 m0, s37
	s_nop 0
	global_load_lds_dwordx4 v[142:143], off
	s_waitcnt vmcnt(8)
	s_waitcnt lgkmcnt(0)
	s_barrier
	s_setprio 1
	s_waitcnt lgkmcnt(0)
	v_mfma_f32_16x16x32_bf16 v[126:129], v[156:159], v[190:193], v[126:129]
	v_mfma_f32_16x16x32_bf16 v[122:125], v[164:167], v[190:193], v[122:125]
	v_mfma_f32_16x16x32_bf16 v[118:121], v[156:159], v[208:211], v[118:121]
	v_mfma_f32_16x16x32_bf16 v[110:113], v[164:167], v[208:211], v[110:113]
	v_mfma_f32_16x16x32_bf16 v[102:105], v[156:159], v[216:219], v[102:105]
	v_mfma_f32_16x16x32_bf16 v[94:97], v[164:167], v[216:219], v[94:97]
	v_mfma_f32_16x16x32_bf16 v[82:85], v[156:159], v[224:227], v[82:85]
	v_mfma_f32_16x16x32_bf16 v[74:77], v[164:167], v[224:227], v[74:77]
	v_mfma_f32_16x16x32_bf16 v[126:129], v[160:163], v[204:207], v[126:129]
	v_mfma_f32_16x16x32_bf16 v[122:125], v[168:171], v[204:207], v[122:125]
	v_mfma_f32_16x16x32_bf16 v[118:121], v[160:163], v[212:215], v[118:121]
	v_mfma_f32_16x16x32_bf16 v[110:113], v[168:171], v[212:215], v[110:113]
	v_mfma_f32_16x16x32_bf16 v[102:105], v[160:163], v[220:223], v[102:105]
	v_mfma_f32_16x16x32_bf16 v[94:97], v[168:171], v[220:223], v[94:97]
	v_mfma_f32_16x16x32_bf16 v[82:85], v[160:163], v[234:237], v[82:85]
	v_mfma_f32_16x16x32_bf16 v[74:77], v[168:171], v[234:237], v[74:77]
	v_mfma_f32_16x16x32_bf16 v[114:117], v[172:175], v[190:193], v[114:117]
	v_mfma_f32_16x16x32_bf16 v[106:109], v[180:183], v[190:193], v[106:109]
	v_mfma_f32_16x16x32_bf16 v[98:101], v[172:175], v[208:211], v[98:101]
	v_mfma_f32_16x16x32_bf16 v[90:93], v[180:183], v[208:211], v[90:93]
	v_mfma_f32_16x16x32_bf16 v[86:89], v[172:175], v[216:219], v[86:89]
	v_mfma_f32_16x16x32_bf16 v[78:81], v[180:183], v[216:219], v[78:81]
	v_mfma_f32_16x16x32_bf16 v[70:73], v[172:175], v[224:227], v[70:73]
	v_mfma_f32_16x16x32_bf16 v[66:69], v[180:183], v[224:227], v[66:69]
	s_barrier
	s_setprio 2
	v_mfma_f32_16x16x32_bf16 v[114:117], v[176:179], v[204:207], v[114:117]
	ds_read_b128 v[190:193], v148 offset:16384
	v_mfma_f32_16x16x32_bf16 v[106:109], v[184:187], v[204:207], v[106:109]
	v_mfma_f32_16x16x32_bf16 v[98:101], v[176:179], v[212:215], v[98:101]
	v_mfma_f32_16x16x32_bf16 v[90:93], v[184:187], v[212:215], v[90:93]
	ds_read_b128 v[204:207], v148 offset:17408
	ds_read_b128 v[208:211], v148 offset:18432
	v_mfma_f32_16x16x32_bf16 v[86:89], v[176:179], v[220:223], v[86:89]
	v_mfma_f32_16x16x32_bf16 v[78:81], v[184:187], v[220:223], v[78:81]
	ds_read_b128 v[212:215], v148 offset:19456
	ds_read_b128 v[216:219], v148 offset:20480
	v_mfma_f32_16x16x32_bf16 v[70:73], v[176:179], v[234:237], v[70:73]
	v_mfma_f32_16x16x32_bf16 v[66:69], v[184:187], v[234:237], v[66:69]
	ds_read_b128 v[220:223], v148 offset:21504
	ds_read_b128 v[224:227], v148 offset:22528
	s_setprio 0
	s_mov_b32 m0, s38
	v_lshl_add_u64 v[142:143], s[28:29], 0, v[134:135]
	s_add_u32 s52, s28, 0x20000
	ds_read_b128 v[234:237], v148 offset:23552
	global_load_lds_dwordx4 v[142:143], off
	v_lshl_add_u64 v[152:153], s[28:29], 0, v[130:131]
	s_mov_b32 m0, s39
	s_addc_u32 s53, s29, 0
	global_load_lds_dwordx4 v[152:153], off
	v_lshl_add_u64 v[194:195], s[52:53], 0, v[134:135]
	s_mov_b32 m0, s40
	v_lshl_add_u64 v[200:201], s[30:31], 0, v[132:133]
	global_load_lds_dwordx4 v[194:195], off
	v_lshl_add_u64 v[194:195], s[52:53], 0, v[130:131]
	s_mov_b32 m0, s41
	s_nop 0
	global_load_lds_dwordx4 v[194:195], off
	v_lshl_add_u64 v[194:195], s[30:31], 0, v[136:137]
	s_mov_b32 m0, s9
	s_nop 0
	global_load_lds_dwordx4 v[194:195], off
	s_mov_b32 m0, s13
	s_nop 0
	global_load_lds_dwordx4 v[200:201], off
	s_waitcnt vmcnt(8)
	s_waitcnt lgkmcnt(0)
	s_barrier
	s_setprio 1
	s_waitcnt lgkmcnt(0)
	v_mfma_f32_16x16x32_bf16 v[62:65], v[156:159], v[190:193], v[62:65]
	v_mfma_f32_16x16x32_bf16 v[58:61], v[164:167], v[190:193], v[58:61]
	v_mfma_f32_16x16x32_bf16 v[54:57], v[156:159], v[208:211], v[54:57]
	v_mfma_f32_16x16x32_bf16 v[46:49], v[164:167], v[208:211], v[46:49]
	v_mfma_f32_16x16x32_bf16 v[38:41], v[156:159], v[216:219], v[38:41]
	v_mfma_f32_16x16x32_bf16 v[30:33], v[164:167], v[216:219], v[30:33]
	v_mfma_f32_16x16x32_bf16 v[22:25], v[156:159], v[224:227], v[22:25]
	v_mfma_f32_16x16x32_bf16 v[14:17], v[164:167], v[224:227], v[14:17]
	v_mfma_f32_16x16x32_bf16 v[62:65], v[160:163], v[204:207], v[62:65]
	v_mfma_f32_16x16x32_bf16 v[58:61], v[168:171], v[204:207], v[58:61]
	v_mfma_f32_16x16x32_bf16 v[54:57], v[160:163], v[212:215], v[54:57]
	v_mfma_f32_16x16x32_bf16 v[46:49], v[168:171], v[212:215], v[46:49]
	v_mfma_f32_16x16x32_bf16 v[38:41], v[160:163], v[220:223], v[38:41]
	v_mfma_f32_16x16x32_bf16 v[30:33], v[168:171], v[220:223], v[30:33]
	v_mfma_f32_16x16x32_bf16 v[22:25], v[160:163], v[234:237], v[22:25]
	v_mfma_f32_16x16x32_bf16 v[14:17], v[168:171], v[234:237], v[14:17]
	v_mfma_f32_16x16x32_bf16 v[50:53], v[172:175], v[190:193], v[50:53]
	v_mfma_f32_16x16x32_bf16 v[42:45], v[180:183], v[190:193], v[42:45]
	v_mfma_f32_16x16x32_bf16 v[34:37], v[172:175], v[208:211], v[34:37]
	v_mfma_f32_16x16x32_bf16 v[26:29], v[180:183], v[208:211], v[26:29]
	v_mfma_f32_16x16x32_bf16 v[18:21], v[172:175], v[216:219], v[18:21]
	v_mfma_f32_16x16x32_bf16 v[10:13], v[180:183], v[216:219], v[10:13]
	v_mfma_f32_16x16x32_bf16 v[6:9], v[172:175], v[224:227], v[6:9]
	v_mfma_f32_16x16x32_bf16 v[2:5], v[180:183], v[224:227], v[2:5]
	s_barrier
	s_setprio 2
	v_mfma_f32_16x16x32_bf16 v[50:53], v[176:179], v[204:207], v[50:53]
	ds_read_b128 v[156:159], v149
	ds_read_b128 v[160:163], v149 offset:1024
	ds_read_b128 v[164:167], v149 offset:2048
	ds_read_b128 v[168:171], v149 offset:3072
	ds_read_b128 v[172:175], v150
	v_mfma_f32_16x16x32_bf16 v[42:45], v[184:187], v[204:207], v[42:45]
	v_mfma_f32_16x16x32_bf16 v[34:37], v[176:179], v[212:215], v[34:37]
	v_mfma_f32_16x16x32_bf16 v[26:29], v[184:187], v[212:215], v[26:29]
	v_mfma_f32_16x16x32_bf16 v[18:21], v[176:179], v[220:223], v[18:21]
	v_mfma_f32_16x16x32_bf16 v[10:13], v[184:187], v[220:223], v[10:13]
	v_mfma_f32_16x16x32_bf16 v[6:9], v[176:179], v[234:237], v[6:9]
	v_mfma_f32_16x16x32_bf16 v[2:5], v[184:187], v[234:237], v[2:5]
	s_setprio 0
	ds_read_b128 v[176:179], v150 offset:1024
	ds_read_b128 v[180:183], v150 offset:2048
	ds_read_b128 v[184:187], v150 offset:3072
	s_add_u32 s30, s30, 0x100000
	s_addc_u32 s31, s31, 0
	s_mov_b32 m0, s14
	v_lshl_add_u64 v[238:239], s[30:31], 0, v[136:137]
	ds_read_b128 v[190:193], v148 offset:32768
	ds_read_b128 v[204:207], v148 offset:33792
	ds_read_b128 v[208:211], v148 offset:34816
	ds_read_b128 v[212:215], v148 offset:35840
	ds_read_b128 v[216:219], v148 offset:36864
	ds_read_b128 v[220:223], v148 offset:37888
	ds_read_b128 v[224:227], v148 offset:38912
	ds_read_b128 v[234:237], v148 offset:39936
	global_load_lds_dwordx4 v[238:239], off
	v_lshl_add_u64 v[238:239], s[30:31], 0, v[132:133]
	s_mov_b32 m0, s15
	s_nop 0
	global_load_lds_dwordx4 v[238:239], off
	s_waitcnt vmcnt(8)
	s_waitcnt lgkmcnt(0)
	s_barrier
	s_setprio 1
	s_waitcnt lgkmcnt(0)
	v_mfma_f32_16x16x32_bf16 v[126:129], v[156:159], v[190:193], v[126:129]
	v_mfma_f32_16x16x32_bf16 v[122:125], v[164:167], v[190:193], v[122:125]
	v_mfma_f32_16x16x32_bf16 v[118:121], v[156:159], v[208:211], v[118:121]
	v_mfma_f32_16x16x32_bf16 v[110:113], v[164:167], v[208:211], v[110:113]
	v_mfma_f32_16x16x32_bf16 v[102:105], v[156:159], v[216:219], v[102:105]
	v_mfma_f32_16x16x32_bf16 v[94:97], v[164:167], v[216:219], v[94:97]
	v_mfma_f32_16x16x32_bf16 v[82:85], v[156:159], v[224:227], v[82:85]
	v_mfma_f32_16x16x32_bf16 v[74:77], v[164:167], v[224:227], v[74:77]
	v_mfma_f32_16x16x32_bf16 v[126:129], v[160:163], v[204:207], v[126:129]
	v_mfma_f32_16x16x32_bf16 v[122:125], v[168:171], v[204:207], v[122:125]
	v_mfma_f32_16x16x32_bf16 v[118:121], v[160:163], v[212:215], v[118:121]
	v_mfma_f32_16x16x32_bf16 v[110:113], v[168:171], v[212:215], v[110:113]
	v_mfma_f32_16x16x32_bf16 v[102:105], v[160:163], v[220:223], v[102:105]
	v_mfma_f32_16x16x32_bf16 v[94:97], v[168:171], v[220:223], v[94:97]
	v_mfma_f32_16x16x32_bf16 v[82:85], v[160:163], v[234:237], v[82:85]
	v_mfma_f32_16x16x32_bf16 v[74:77], v[168:171], v[234:237], v[74:77]
	v_mfma_f32_16x16x32_bf16 v[114:117], v[172:175], v[190:193], v[114:117]
	v_mfma_f32_16x16x32_bf16 v[106:109], v[180:183], v[190:193], v[106:109]
	v_mfma_f32_16x16x32_bf16 v[98:101], v[172:175], v[208:211], v[98:101]
	v_mfma_f32_16x16x32_bf16 v[90:93], v[180:183], v[208:211], v[90:93]
	v_mfma_f32_16x16x32_bf16 v[86:89], v[172:175], v[216:219], v[86:89]
	v_mfma_f32_16x16x32_bf16 v[78:81], v[180:183], v[216:219], v[78:81]
	v_mfma_f32_16x16x32_bf16 v[70:73], v[172:175], v[224:227], v[70:73]
	v_mfma_f32_16x16x32_bf16 v[66:69], v[180:183], v[224:227], v[66:69]
	s_barrier
	s_setprio 2
	v_mfma_f32_16x16x32_bf16 v[114:117], v[176:179], v[204:207], v[114:117]
	ds_read_b128 v[190:193], v148 offset:49152
	v_mfma_f32_16x16x32_bf16 v[106:109], v[184:187], v[204:207], v[106:109]
	v_mfma_f32_16x16x32_bf16 v[98:101], v[176:179], v[212:215], v[98:101]
	v_mfma_f32_16x16x32_bf16 v[90:93], v[184:187], v[212:215], v[90:93]
	ds_read_b128 v[204:207], v148 offset:50176
	ds_read_b128 v[208:211], v148 offset:51200
	v_mfma_f32_16x16x32_bf16 v[86:89], v[176:179], v[220:223], v[86:89]
	v_mfma_f32_16x16x32_bf16 v[78:81], v[184:187], v[220:223], v[78:81]
	ds_read_b128 v[212:215], v148 offset:52224
	ds_read_b128 v[216:219], v148 offset:53248
	v_mfma_f32_16x16x32_bf16 v[70:73], v[176:179], v[234:237], v[70:73]
	v_mfma_f32_16x16x32_bf16 v[66:69], v[184:187], v[234:237], v[66:69]
	ds_read_b128 v[220:223], v148 offset:54272
	ds_read_b128 v[224:227], v148 offset:55296
	s_setprio 0
	s_mov_b32 m0, s42
	v_lshl_add_u64 v[142:143], v[142:143], 0, s[4:5]
	s_add_u32 s28, s28, 0x20080
	ds_read_b128 v[234:237], v148 offset:56320
	global_load_lds_dwordx4 v[142:143], off
	v_lshl_add_u64 v[142:143], v[152:153], 0, s[4:5]
	s_mov_b32 m0, s43
	s_addc_u32 s29, s29, 0
	global_load_lds_dwordx4 v[142:143], off
	v_lshl_add_u64 v[142:143], s[28:29], 0, v[134:135]
	s_mov_b32 m0, s44
	s_nop 0
	global_load_lds_dwordx4 v[142:143], off
	v_lshl_add_u64 v[142:143], s[28:29], 0, v[130:131]
	s_mov_b32 m0, s45
	s_nop 0
	global_load_lds_dwordx4 v[142:143], off
	v_lshl_add_u64 v[142:143], v[194:195], 0, s[4:5]
	s_mov_b32 m0, s34
	s_nop 0
	global_load_lds_dwordx4 v[142:143], off
	v_lshl_add_u64 v[142:143], v[200:201], 0, s[4:5]
	s_mov_b32 m0, s35
	s_nop 0
	global_load_lds_dwordx4 v[142:143], off
	s_waitcnt vmcnt(8)
	s_waitcnt lgkmcnt(0)
	s_barrier
	s_setprio 1
	s_waitcnt lgkmcnt(0)
	v_mfma_f32_16x16x32_bf16 v[62:65], v[156:159], v[190:193], v[62:65]
	v_mfma_f32_16x16x32_bf16 v[58:61], v[164:167], v[190:193], v[58:61]
	v_mfma_f32_16x16x32_bf16 v[54:57], v[156:159], v[208:211], v[54:57]
	v_mfma_f32_16x16x32_bf16 v[46:49], v[164:167], v[208:211], v[46:49]
	v_mfma_f32_16x16x32_bf16 v[38:41], v[156:159], v[216:219], v[38:41]
	v_mfma_f32_16x16x32_bf16 v[30:33], v[164:167], v[216:219], v[30:33]
	v_mfma_f32_16x16x32_bf16 v[22:25], v[156:159], v[224:227], v[22:25]
	v_mfma_f32_16x16x32_bf16 v[14:17], v[164:167], v[224:227], v[14:17]
	v_mfma_f32_16x16x32_bf16 v[62:65], v[160:163], v[204:207], v[62:65]
	v_mfma_f32_16x16x32_bf16 v[58:61], v[168:171], v[204:207], v[58:61]
	v_mfma_f32_16x16x32_bf16 v[54:57], v[160:163], v[212:215], v[54:57]
	v_mfma_f32_16x16x32_bf16 v[46:49], v[168:171], v[212:215], v[46:49]
	v_mfma_f32_16x16x32_bf16 v[38:41], v[160:163], v[220:223], v[38:41]
	v_mfma_f32_16x16x32_bf16 v[30:33], v[168:171], v[220:223], v[30:33]
	v_mfma_f32_16x16x32_bf16 v[22:25], v[160:163], v[234:237], v[22:25]
	v_mfma_f32_16x16x32_bf16 v[14:17], v[168:171], v[234:237], v[14:17]
	v_mfma_f32_16x16x32_bf16 v[50:53], v[172:175], v[190:193], v[50:53]
	v_mfma_f32_16x16x32_bf16 v[42:45], v[180:183], v[190:193], v[42:45]
	v_mfma_f32_16x16x32_bf16 v[34:37], v[172:175], v[208:211], v[34:37]
	v_mfma_f32_16x16x32_bf16 v[26:29], v[180:183], v[208:211], v[26:29]
	v_mfma_f32_16x16x32_bf16 v[18:21], v[172:175], v[216:219], v[18:21]
	v_mfma_f32_16x16x32_bf16 v[10:13], v[180:183], v[216:219], v[10:13]
	v_mfma_f32_16x16x32_bf16 v[6:9], v[172:175], v[224:227], v[6:9]
	v_mfma_f32_16x16x32_bf16 v[2:5], v[180:183], v[224:227], v[2:5]
	v_mfma_f32_16x16x32_bf16 v[50:53], v[176:179], v[204:207], v[50:53]
	v_mfma_f32_16x16x32_bf16 v[42:45], v[184:187], v[204:207], v[42:45]
	v_mfma_f32_16x16x32_bf16 v[34:37], v[176:179], v[212:215], v[34:37]
	v_mfma_f32_16x16x32_bf16 v[26:29], v[184:187], v[212:215], v[26:29]
	s_barrier
	s_setprio 2
	v_mfma_f32_16x16x32_bf16 v[18:21], v[176:179], v[220:223], v[18:21]
	v_mfma_f32_16x16x32_bf16 v[10:13], v[184:187], v[220:223], v[10:13]
	v_mfma_f32_16x16x32_bf16 v[6:9], v[176:179], v[234:237], v[6:9]
	v_mfma_f32_16x16x32_bf16 v[2:5], v[184:187], v[234:237], v[2:5]
	s_setprio 0
	s_add_i32 s50, s50, 2
	s_add_u32 s26, s26, 0x100
	s_addc_u32 s27, s27, 0
	s_add_u32 s23, s23, 0x100
	s_addc_u32 s49, s49, 0
	s_cmp_gt_u32 s50, 5
	s_cbranch_scc0 .LBB0_514
	s_and_b64 vcc, exec, s[6:7]
	s_cbranch_vccz .LBB0_517
	s_barrier

.LBB0_734:
	ds_read_b128 v[158:161], v227
	ds_read_b128 v[154:157], v227 offset:1024
	ds_read_b128 v[150:153], v227 offset:2048
	ds_read_b128 v[146:149], v227 offset:3072
	ds_read_b128 v[62:65], v233
	ds_read_b128 v[58:61], v233 offset:1024
	ds_read_b128 v[54:57], v233 offset:2048
	ds_read_b128 v[50:53], v233 offset:3072
	s_add_u32 s14, s30, s34
	s_addc_u32 s15, s31, s35
	s_add_u32 s14, s14, 0x100
	s_addc_u32 s15, s15, 0
	s_add_u32 s25, s77, s34
	s_addc_u32 s29, s78, s35
	s_cmpk_eq_i32 s34, 0xf00
	s_cselect_b32 s41, s31, s15
	s_cselect_b32 s40, s30, s14
	s_cselect_b32 s39, s1, s29
	s_cselect_b32 s38, s0, s25
	s_add_i32 s66, s23, 0xc000
	v_lshl_add_u64 v[240:241], v[162:163], 0, s[34:35]
	s_mov_b32 m0, s66
	s_add_i32 s67, s23, 0xe000
	ds_read_b128 v[166:169], v226
	ds_read_b128 v[170:173], v226 offset:1024
	ds_read_b128 v[174:177], v226 offset:2048
	ds_read_b128 v[178:181], v226 offset:3072
	ds_read_b128 v[182:185], v226 offset:4096
	ds_read_b128 v[186:189], v226 offset:5120
	ds_read_b128 v[190:193], v226 offset:6144
	ds_read_b128 v[236:239], v226 offset:7168
	global_load_lds_dwordx4 v[240:241], off
	v_lshl_add_u64 v[240:241], v[164:165], 0, s[34:35]
	s_mov_b32 m0, s67
	s_nop 0
	global_load_lds_dwordx4 v[240:241], off
	s_waitcnt vmcnt(8)
	s_waitcnt lgkmcnt(0)
	s_barrier
	s_setprio 1
	s_waitcnt lgkmcnt(0)
	v_mfma_i32_16x16x64_i8 v[142:145], v[158:161], v[166:169], v[142:145]
	v_mfma_i32_16x16x64_i8 v[142:145], v[154:157], v[170:173], v[142:145]
	v_mfma_i32_16x16x64_i8 v[138:141], v[150:153], v[166:169], v[138:141]
	v_mfma_i32_16x16x64_i8 v[138:141], v[146:149], v[170:173], v[138:141]
	v_mfma_i32_16x16x64_i8 v[126:129], v[158:161], v[174:177], v[126:129]
	v_mfma_i32_16x16x64_i8 v[126:129], v[154:157], v[178:181], v[126:129]
	v_mfma_i32_16x16x64_i8 v[122:125], v[150:153], v[174:177], v[122:125]
	v_mfma_i32_16x16x64_i8 v[122:125], v[146:149], v[178:181], v[122:125]
	v_mfma_i32_16x16x64_i8 v[110:113], v[158:161], v[182:185], v[110:113]
	v_mfma_i32_16x16x64_i8 v[110:113], v[154:157], v[186:189], v[110:113]
	v_mfma_i32_16x16x64_i8 v[106:109], v[150:153], v[182:185], v[106:109]
	v_mfma_i32_16x16x64_i8 v[106:109], v[146:149], v[186:189], v[106:109]
	v_mfma_i32_16x16x64_i8 v[94:97], v[158:161], v[190:193], v[94:97]
	v_mfma_i32_16x16x64_i8 v[94:97], v[154:157], v[236:239], v[94:97]
	v_mfma_i32_16x16x64_i8 v[90:93], v[150:153], v[190:193], v[90:93]
	v_mfma_i32_16x16x64_i8 v[90:93], v[146:149], v[236:239], v[90:93]
	v_mfma_i32_16x16x64_i8 v[134:137], v[62:65], v[166:169], v[134:137]
	v_mfma_i32_16x16x64_i8 v[134:137], v[58:61], v[170:173], v[134:137]
	v_mfma_i32_16x16x64_i8 v[130:133], v[54:57], v[166:169], v[130:133]
	v_mfma_i32_16x16x64_i8 v[130:133], v[50:53], v[170:173], v[130:133]
	v_mfma_i32_16x16x64_i8 v[118:121], v[62:65], v[174:177], v[118:121]
	v_mfma_i32_16x16x64_i8 v[118:121], v[58:61], v[178:181], v[118:121]
	v_mfma_i32_16x16x64_i8 v[114:117], v[54:57], v[174:177], v[114:117]
	v_mfma_i32_16x16x64_i8 v[114:117], v[50:53], v[178:181], v[114:117]
	s_barrier
	s_setprio 2
	v_mfma_i32_16x16x64_i8 v[102:105], v[62:65], v[182:185], v[102:105]
	ds_read_b128 v[174:177], v226 offset:16384
	ds_read_b128 v[178:181], v226 offset:17408
	v_mfma_i32_16x16x64_i8 v[102:105], v[58:61], v[186:189], v[102:105]
	v_mfma_i32_16x16x64_i8 v[98:101], v[54:57], v[182:185], v[98:101]
	v_mfma_i32_16x16x64_i8 v[98:101], v[50:53], v[186:189], v[98:101]
	v_mfma_i32_16x16x64_i8 v[86:89], v[62:65], v[190:193], v[86:89]
	ds_read_b128 v[182:185], v226 offset:18432
	v_mfma_i32_16x16x64_i8 v[86:89], v[58:61], v[236:239], v[86:89]
	ds_read_b128 v[186:189], v226 offset:19456
	v_mfma_i32_16x16x64_i8 v[82:85], v[54:57], v[190:193], v[82:85]
	v_mfma_i32_16x16x64_i8 v[82:85], v[50:53], v[236:239], v[82:85]
	s_setprio 0
	s_add_i32 s68, s60, s21
	s_add_i32 s69, s68, 0x2000
	v_lshl_add_u64 v[166:167], s[38:39], 0, v[202:203]
	s_mov_b32 m0, s68
	s_add_u32 s14, s38, 0x80000
	ds_read_b128 v[190:193], v226 offset:20480
	ds_read_b128 v[236:239], v226 offset:21504
	ds_read_b128 v[240:243], v226 offset:22528
	ds_read_b128 v[244:247], v226 offset:23552
	global_load_lds_dwordx4 v[166:167], off
	v_lshl_add_u64 v[168:169], s[38:39], 0, v[206:207]
	s_mov_b32 m0, s69
	s_addc_u32 s15, s39, 0
	s_add_i32 s70, s61, s21
	global_load_lds_dwordx4 v[168:169], off
	v_lshl_add_u64 v[170:171], s[14:15], 0, v[202:203]
	s_mov_b32 m0, s70
	s_add_i32 s71, s70, 0x2000
	global_load_lds_dwordx4 v[170:171], off
	v_lshl_add_u64 v[170:171], s[14:15], 0, v[206:207]
	s_mov_b32 m0, s71
	v_lshl_add_u64 v[172:173], s[40:41], 0, v[204:205]
	global_load_lds_dwordx4 v[170:171], off
	v_lshl_add_u64 v[170:171], s[40:41], 0, v[194:195]
	s_mov_b32 m0, s23
	s_nop 0
	global_load_lds_dwordx4 v[170:171], off
	s_mov_b32 m0, s42
	s_nop 0
	global_load_lds_dwordx4 v[172:173], off
	s_waitcnt vmcnt(8)
	s_waitcnt lgkmcnt(0)
	s_barrier
	s_setprio 1
	s_waitcnt lgkmcnt(0)
	v_mfma_i32_16x16x64_i8 v[78:81], v[158:161], v[174:177], v[78:81]
	v_mfma_i32_16x16x64_i8 v[78:81], v[154:157], v[178:181], v[78:81]
	v_mfma_i32_16x16x64_i8 v[74:77], v[150:153], v[174:177], v[74:77]
	v_mfma_i32_16x16x64_i8 v[74:77], v[146:149], v[178:181], v[74:77]
	v_mfma_i32_16x16x64_i8 v[46:49], v[158:161], v[182:185], v[46:49]
	v_mfma_i32_16x16x64_i8 v[46:49], v[154:157], v[186:189], v[46:49]
	v_mfma_i32_16x16x64_i8 v[42:45], v[150:153], v[182:185], v[42:45]
	v_mfma_i32_16x16x64_i8 v[42:45], v[146:149], v[186:189], v[42:45]
	v_mfma_i32_16x16x64_i8 v[30:33], v[158:161], v[190:193], v[30:33]
	v_mfma_i32_16x16x64_i8 v[30:33], v[154:157], v[236:239], v[30:33]
	v_mfma_i32_16x16x64_i8 v[26:29], v[150:153], v[190:193], v[26:29]
	v_mfma_i32_16x16x64_i8 v[26:29], v[146:149], v[236:239], v[26:29]
	v_mfma_i32_16x16x64_i8 v[14:17], v[158:161], v[240:243], v[14:17]
	v_mfma_i32_16x16x64_i8 v[14:17], v[154:157], v[244:247], v[14:17]
	v_mfma_i32_16x16x64_i8 v[10:13], v[150:153], v[240:243], v[10:13]
	v_mfma_i32_16x16x64_i8 v[10:13], v[146:149], v[244:247], v[10:13]
	v_mfma_i32_16x16x64_i8 v[70:73], v[62:65], v[174:177], v[70:73]
	v_mfma_i32_16x16x64_i8 v[70:73], v[58:61], v[178:181], v[70:73]
	v_mfma_i32_16x16x64_i8 v[66:69], v[54:57], v[174:177], v[66:69]
	v_mfma_i32_16x16x64_i8 v[66:69], v[50:53], v[178:181], v[66:69]
	v_mfma_i32_16x16x64_i8 v[38:41], v[62:65], v[182:185], v[38:41]
	v_mfma_i32_16x16x64_i8 v[38:41], v[58:61], v[186:189], v[38:41]
	v_mfma_i32_16x16x64_i8 v[34:37], v[54:57], v[182:185], v[34:37]
	v_mfma_i32_16x16x64_i8 v[34:37], v[50:53], v[186:189], v[34:37]
	s_barrier
	s_setprio 2
	v_mfma_i32_16x16x64_i8 v[22:25], v[62:65], v[190:193], v[22:25]
	v_mfma_i32_16x16x64_i8 v[22:25], v[58:61], v[236:239], v[22:25]
	v_mfma_i32_16x16x64_i8 v[18:21], v[54:57], v[190:193], v[18:21]
	v_mfma_i32_16x16x64_i8 v[18:21], v[50:53], v[236:239], v[18:21]
	v_mfma_i32_16x16x64_i8 v[6:9], v[62:65], v[240:243], v[6:9]
	v_mfma_i32_16x16x64_i8 v[6:9], v[58:61], v[244:247], v[6:9]
	v_mfma_i32_16x16x64_i8 v[2:5], v[54:57], v[240:243], v[2:5]
	v_mfma_i32_16x16x64_i8 v[2:5], v[50:53], v[244:247], v[2:5]
	s_setprio 0
	s_add_i32 s72, 0, 0x18000
	v_add_u32_e32 v235, s72, v225
	s_add_i32 s74, 0, 0x1c000
	v_add_u32_e32 v236, s74, v225
	ds_read_b128 v[50:53], v235
	ds_read_b128 v[54:57], v235 offset:1024
	ds_read_b128 v[58:61], v235 offset:2048
	ds_read_b128 v[62:65], v235 offset:3072
	ds_read_b128 v[146:149], v236
	ds_read_b128 v[150:153], v236 offset:1024
	ds_read_b128 v[154:157], v236 offset:2048
	ds_read_b128 v[158:161], v236 offset:3072
	s_add_u32 s14, s40, 0x80000
	s_addc_u32 s15, s41, 0
	s_mov_b32 m0, s43
	v_lshl_add_u64 v[250:251], s[14:15], 0, v[194:195]
	ds_read_b128 v[174:177], v226 offset:32768
	ds_read_b128 v[178:181], v226 offset:33792
	ds_read_b128 v[182:185], v226 offset:34816
	ds_read_b128 v[186:189], v226 offset:35840
	ds_read_b128 v[190:193], v226 offset:36864
	ds_read_b128 v[238:241], v226 offset:37888
	ds_read_b128 v[242:245], v226 offset:38912
	ds_read_b128 v[246:249], v226 offset:39936
	global_load_lds_dwordx4 v[250:251], off
	v_lshl_add_u64 v[250:251], s[14:15], 0, v[204:205]
	s_mov_b32 m0, s44
	s_nop 0
	global_load_lds_dwordx4 v[250:251], off
	s_waitcnt vmcnt(8)
	s_waitcnt lgkmcnt(0)
	s_barrier
	s_setprio 1
	s_waitcnt lgkmcnt(0)
	v_mfma_i32_16x16x64_i8 v[142:145], v[50:53], v[174:177], v[142:145]
	v_mfma_i32_16x16x64_i8 v[142:145], v[54:57], v[178:181], v[142:145]
	v_mfma_i32_16x16x64_i8 v[138:141], v[58:61], v[174:177], v[138:141]
	v_mfma_i32_16x16x64_i8 v[138:141], v[62:65], v[178:181], v[138:141]
	v_mfma_i32_16x16x64_i8 v[126:129], v[50:53], v[182:185], v[126:129]
	v_mfma_i32_16x16x64_i8 v[126:129], v[54:57], v[186:189], v[126:129]
	v_mfma_i32_16x16x64_i8 v[122:125], v[58:61], v[182:185], v[122:125]
	v_mfma_i32_16x16x64_i8 v[122:125], v[62:65], v[186:189], v[122:125]
	v_mfma_i32_16x16x64_i8 v[110:113], v[50:53], v[190:193], v[110:113]
	v_mfma_i32_16x16x64_i8 v[110:113], v[54:57], v[238:241], v[110:113]
	v_mfma_i32_16x16x64_i8 v[106:109], v[58:61], v[190:193], v[106:109]
	v_mfma_i32_16x16x64_i8 v[106:109], v[62:65], v[238:241], v[106:109]
	v_mfma_i32_16x16x64_i8 v[94:97], v[50:53], v[242:245], v[94:97]
	v_mfma_i32_16x16x64_i8 v[94:97], v[54:57], v[246:249], v[94:97]
	v_mfma_i32_16x16x64_i8 v[90:93], v[58:61], v[242:245], v[90:93]
	v_mfma_i32_16x16x64_i8 v[90:93], v[62:65], v[246:249], v[90:93]
	v_mfma_i32_16x16x64_i8 v[134:137], v[146:149], v[174:177], v[134:137]
	v_mfma_i32_16x16x64_i8 v[134:137], v[150:153], v[178:181], v[134:137]
	v_mfma_i32_16x16x64_i8 v[130:133], v[154:157], v[174:177], v[130:133]
	v_mfma_i32_16x16x64_i8 v[130:133], v[158:161], v[178:181], v[130:133]
	v_mfma_i32_16x16x64_i8 v[118:121], v[146:149], v[182:185], v[118:121]
	v_mfma_i32_16x16x64_i8 v[118:121], v[150:153], v[186:189], v[118:121]
	v_mfma_i32_16x16x64_i8 v[114:117], v[154:157], v[182:185], v[114:117]
	v_mfma_i32_16x16x64_i8 v[114:117], v[158:161], v[186:189], v[114:117]
	s_barrier
	s_setprio 2
	v_mfma_i32_16x16x64_i8 v[102:105], v[146:149], v[190:193], v[102:105]
	ds_read_b128 v[174:177], v226 offset:49152
	ds_read_b128 v[178:181], v226 offset:50176
	ds_read_b128 v[182:185], v226 offset:51200
	ds_read_b128 v[186:189], v226 offset:52224
	v_mfma_i32_16x16x64_i8 v[102:105], v[150:153], v[238:241], v[102:105]
	v_mfma_i32_16x16x64_i8 v[98:101], v[154:157], v[190:193], v[98:101]
	v_mfma_i32_16x16x64_i8 v[98:101], v[158:161], v[238:241], v[98:101]
	v_mfma_i32_16x16x64_i8 v[86:89], v[146:149], v[242:245], v[86:89]
	ds_read_b128 v[190:193], v226 offset:53248
	v_mfma_i32_16x16x64_i8 v[86:89], v[150:153], v[246:249], v[86:89]
	ds_read_b128 v[238:241], v226 offset:54272
	v_mfma_i32_16x16x64_i8 v[82:85], v[154:157], v[242:245], v[82:85]
	v_mfma_i32_16x16x64_i8 v[82:85], v[158:161], v[246:249], v[82:85]
	s_setprio 0
	s_add_i32 s72, s72, s21
	s_add_i32 s73, s72, 0x2000
	v_lshl_add_u64 v[166:167], v[166:167], 0, s[6:7]
	s_mov_b32 m0, s72
	s_add_u32 s14, s38, 0x80080
	ds_read_b128 v[242:245], v226 offset:55296
	ds_read_b128 v[246:249], v226 offset:56320
	global_load_lds_dwordx4 v[166:167], off
	v_lshl_add_u64 v[166:167], v[168:169], 0, s[6:7]
	s_mov_b32 m0, s73
	s_addc_u32 s15, s39, 0
	s_add_i32 s74, s74, s21
	global_load_lds_dwordx4 v[166:167], off
	v_lshl_add_u64 v[166:167], s[14:15], 0, v[202:203]
	s_mov_b32 m0, s74
	s_add_i32 s75, s74, 0x2000
	global_load_lds_dwordx4 v[166:167], off
	v_lshl_add_u64 v[166:167], s[14:15], 0, v[206:207]
	s_mov_b32 m0, s75
	s_nop 0
	global_load_lds_dwordx4 v[166:167], off
	v_lshl_add_u64 v[166:167], v[170:171], 0, s[6:7]
	s_mov_b32 m0, s51
	s_nop 0
	global_load_lds_dwordx4 v[166:167], off
	v_lshl_add_u64 v[166:167], v[172:173], 0, s[6:7]
	s_mov_b32 m0, s53
	s_nop 0
	global_load_lds_dwordx4 v[166:167], off
	s_waitcnt vmcnt(8)
	s_waitcnt lgkmcnt(0)
	s_barrier
	s_setprio 1
	s_waitcnt lgkmcnt(0)
	v_mfma_i32_16x16x64_i8 v[78:81], v[50:53], v[174:177], v[78:81]
	v_mfma_i32_16x16x64_i8 v[78:81], v[54:57], v[178:181], v[78:81]
	v_mfma_i32_16x16x64_i8 v[74:77], v[58:61], v[174:177], v[74:77]
	v_mfma_i32_16x16x64_i8 v[74:77], v[62:65], v[178:181], v[74:77]
	v_mfma_i32_16x16x64_i8 v[46:49], v[50:53], v[182:185], v[46:49]
	v_mfma_i32_16x16x64_i8 v[46:49], v[54:57], v[186:189], v[46:49]
	v_mfma_i32_16x16x64_i8 v[42:45], v[58:61], v[182:185], v[42:45]
	v_mfma_i32_16x16x64_i8 v[42:45], v[62:65], v[186:189], v[42:45]
	v_mfma_i32_16x16x64_i8 v[30:33], v[50:53], v[190:193], v[30:33]
	v_mfma_i32_16x16x64_i8 v[30:33], v[54:57], v[238:241], v[30:33]
	v_mfma_i32_16x16x64_i8 v[26:29], v[58:61], v[190:193], v[26:29]
	v_mfma_i32_16x16x64_i8 v[26:29], v[62:65], v[238:241], v[26:29]
	v_mfma_i32_16x16x64_i8 v[14:17], v[50:53], v[242:245], v[14:17]
	v_mfma_i32_16x16x64_i8 v[14:17], v[54:57], v[246:249], v[14:17]
	v_mfma_i32_16x16x64_i8 v[10:13], v[58:61], v[242:245], v[10:13]
	v_mfma_i32_16x16x64_i8 v[10:13], v[62:65], v[246:249], v[10:13]
	v_mfma_i32_16x16x64_i8 v[70:73], v[146:149], v[174:177], v[70:73]
	v_mfma_i32_16x16x64_i8 v[70:73], v[150:153], v[178:181], v[70:73]
	v_mfma_i32_16x16x64_i8 v[66:69], v[154:157], v[174:177], v[66:69]
	v_mfma_i32_16x16x64_i8 v[66:69], v[158:161], v[178:181], v[66:69]
	v_mfma_i32_16x16x64_i8 v[38:41], v[146:149], v[182:185], v[38:41]
	v_mfma_i32_16x16x64_i8 v[38:41], v[150:153], v[186:189], v[38:41]
	v_mfma_i32_16x16x64_i8 v[34:37], v[154:157], v[182:185], v[34:37]
	v_mfma_i32_16x16x64_i8 v[34:37], v[158:161], v[186:189], v[34:37]
	v_mfma_i32_16x16x64_i8 v[22:25], v[146:149], v[190:193], v[22:25]
	v_mfma_i32_16x16x64_i8 v[22:25], v[150:153], v[238:241], v[22:25]
	v_mfma_i32_16x16x64_i8 v[18:21], v[154:157], v[190:193], v[18:21]
	v_mfma_i32_16x16x64_i8 v[18:21], v[158:161], v[238:241], v[18:21]
	s_barrier
	s_setprio 2
	v_mfma_i32_16x16x64_i8 v[6:9], v[146:149], v[242:245], v[6:9]
	v_mfma_i32_16x16x64_i8 v[6:9], v[150:153], v[246:249], v[6:9]
	v_mfma_i32_16x16x64_i8 v[2:5], v[154:157], v[242:245], v[2:5]
	v_mfma_i32_16x16x64_i8 v[2:5], v[158:161], v[246:249], v[2:5]
	s_setprio 0
	s_add_i32 s3, s3, 2
	s_add_u32 s34, s34, 0x100
	s_addc_u32 s35, s35, 0
	s_cmp_gt_u32 s3, 29
	s_cbranch_scc0 .LBB0_734
	s_nop 15
	s_nop 15
	s_and_b64 vcc, exec, s[8:9]
	s_cbranch_vccz .LBB0_737
	s_barrier

.LBB0_740:
	ds_read_b128 v[158:161], v227
	ds_read_b128 v[154:157], v227 offset:1024
	ds_read_b128 v[150:153], v227 offset:2048
	ds_read_b128 v[146:149], v227 offset:3072
	ds_read_b128 v[62:65], v233
	ds_read_b128 v[58:61], v233 offset:1024
	ds_read_b128 v[54:57], v233 offset:2048
	ds_read_b128 v[50:53], v233 offset:3072
	s_add_u32 s36, s38, 0xfff80080
	s_addc_u32 s37, s39, -1
	s_cmp_eq_u32 s33, 28
	s_cselect_b32 s41, s1, s37
	s_cselect_b32 s40, s0, s36
	s_cselect_b32 s37, s15, s29
	s_cselect_b32 s36, s14, s25
	s_mov_b32 m0, s66
	v_lshl_add_u64 v[238:239], s[38:39], 0, v[208:209]
	ds_read_b128 v[162:165], v226
	ds_read_b128 v[166:169], v226 offset:1024
	ds_read_b128 v[170:173], v226 offset:2048
	ds_read_b128 v[174:177], v226 offset:3072
	ds_read_b128 v[178:181], v226 offset:4096
	ds_read_b128 v[182:185], v226 offset:5120
	ds_read_b128 v[186:189], v226 offset:6144
	ds_read_b128 v[190:193], v226 offset:7168
	global_load_lds_dwordx4 v[238:239], off
	v_lshl_add_u64 v[238:239], s[38:39], 0, v[212:213]
	s_mov_b32 m0, s67
	s_nop 0
	global_load_lds_dwordx4 v[238:239], off
	s_waitcnt vmcnt(8)
	s_waitcnt lgkmcnt(0)
	s_barrier
	s_setprio 1
	s_waitcnt lgkmcnt(0)
	v_mfma_i32_16x16x64_i8 v[142:145], v[158:161], v[162:165], v[142:145]
	v_mfma_i32_16x16x64_i8 v[142:145], v[154:157], v[166:169], v[142:145]
	v_mfma_i32_16x16x64_i8 v[138:141], v[150:153], v[162:165], v[138:141]
	v_mfma_i32_16x16x64_i8 v[138:141], v[146:149], v[166:169], v[138:141]
	v_mfma_i32_16x16x64_i8 v[126:129], v[158:161], v[170:173], v[126:129]
	v_mfma_i32_16x16x64_i8 v[126:129], v[154:157], v[174:177], v[126:129]
	v_mfma_i32_16x16x64_i8 v[122:125], v[150:153], v[170:173], v[122:125]
	v_mfma_i32_16x16x64_i8 v[122:125], v[146:149], v[174:177], v[122:125]
	v_mfma_i32_16x16x64_i8 v[110:113], v[158:161], v[178:181], v[110:113]
	v_mfma_i32_16x16x64_i8 v[110:113], v[154:157], v[182:185], v[110:113]
	v_mfma_i32_16x16x64_i8 v[106:109], v[150:153], v[178:181], v[106:109]
	v_mfma_i32_16x16x64_i8 v[106:109], v[146:149], v[182:185], v[106:109]
	v_mfma_i32_16x16x64_i8 v[94:97], v[158:161], v[186:189], v[94:97]
	v_mfma_i32_16x16x64_i8 v[94:97], v[154:157], v[190:193], v[94:97]
	v_mfma_i32_16x16x64_i8 v[90:93], v[150:153], v[186:189], v[90:93]
	v_mfma_i32_16x16x64_i8 v[90:93], v[146:149], v[190:193], v[90:93]
	v_mfma_i32_16x16x64_i8 v[134:137], v[62:65], v[162:165], v[134:137]
	v_mfma_i32_16x16x64_i8 v[134:137], v[58:61], v[166:169], v[134:137]
	v_mfma_i32_16x16x64_i8 v[130:133], v[54:57], v[162:165], v[130:133]
	v_mfma_i32_16x16x64_i8 v[130:133], v[50:53], v[166:169], v[130:133]
	v_mfma_i32_16x16x64_i8 v[118:121], v[62:65], v[170:173], v[118:121]
	v_mfma_i32_16x16x64_i8 v[118:121], v[58:61], v[174:177], v[118:121]
	v_mfma_i32_16x16x64_i8 v[114:117], v[54:57], v[170:173], v[114:117]
	v_mfma_i32_16x16x64_i8 v[114:117], v[50:53], v[174:177], v[114:117]
	s_barrier
	s_setprio 2
	v_mfma_i32_16x16x64_i8 v[102:105], v[62:65], v[178:181], v[102:105]
	ds_read_b128 v[170:173], v226 offset:16384
	ds_read_b128 v[174:177], v226 offset:17408
	v_mfma_i32_16x16x64_i8 v[102:105], v[58:61], v[182:185], v[102:105]
	v_mfma_i32_16x16x64_i8 v[98:101], v[54:57], v[178:181], v[98:101]
	v_mfma_i32_16x16x64_i8 v[98:101], v[50:53], v[182:185], v[98:101]
	v_mfma_i32_16x16x64_i8 v[86:89], v[62:65], v[186:189], v[86:89]
	ds_read_b128 v[178:181], v226 offset:18432
	v_mfma_i32_16x16x64_i8 v[86:89], v[58:61], v[190:193], v[86:89]
	ds_read_b128 v[182:185], v226 offset:19456
	v_mfma_i32_16x16x64_i8 v[82:85], v[54:57], v[186:189], v[82:85]
	v_mfma_i32_16x16x64_i8 v[82:85], v[50:53], v[190:193], v[82:85]
	s_setprio 0
	s_mov_b32 m0, s68
	v_lshl_add_u64 v[162:163], s[36:37], 0, v[202:203]
	s_add_u32 s80, s36, 0x80000
	ds_read_b128 v[186:189], v226 offset:20480
	ds_read_b128 v[190:193], v226 offset:21504
	ds_read_b128 v[238:241], v226 offset:22528
	ds_read_b128 v[242:245], v226 offset:23552
	global_load_lds_dwordx4 v[162:163], off
	v_lshl_add_u64 v[164:165], s[36:37], 0, v[206:207]
	s_mov_b32 m0, s69
	s_addc_u32 s81, s37, 0
	global_load_lds_dwordx4 v[164:165], off
	v_lshl_add_u64 v[166:167], s[80:81], 0, v[202:203]
	s_mov_b32 m0, s70
	v_lshl_add_u64 v[168:169], s[40:41], 0, v[204:205]
	global_load_lds_dwordx4 v[166:167], off
	v_lshl_add_u64 v[166:167], s[80:81], 0, v[206:207]
	s_mov_b32 m0, s71
	s_nop 0
	global_load_lds_dwordx4 v[166:167], off
	v_lshl_add_u64 v[166:167], s[40:41], 0, v[194:195]
	s_mov_b32 m0, s23
	s_nop 0
	global_load_lds_dwordx4 v[166:167], off
	s_mov_b32 m0, s42
	s_nop 0
	global_load_lds_dwordx4 v[168:169], off
	s_waitcnt vmcnt(8)
	s_waitcnt lgkmcnt(0)
	s_barrier
	s_setprio 1
	s_waitcnt lgkmcnt(0)
	v_mfma_i32_16x16x64_i8 v[78:81], v[158:161], v[170:173], v[78:81]
	v_mfma_i32_16x16x64_i8 v[78:81], v[154:157], v[174:177], v[78:81]
	v_mfma_i32_16x16x64_i8 v[74:77], v[150:153], v[170:173], v[74:77]
	v_mfma_i32_16x16x64_i8 v[74:77], v[146:149], v[174:177], v[74:77]
	v_mfma_i32_16x16x64_i8 v[46:49], v[158:161], v[178:181], v[46:49]
	v_mfma_i32_16x16x64_i8 v[46:49], v[154:157], v[182:185], v[46:49]
	v_mfma_i32_16x16x64_i8 v[42:45], v[150:153], v[178:181], v[42:45]
	v_mfma_i32_16x16x64_i8 v[42:45], v[146:149], v[182:185], v[42:45]
	v_mfma_i32_16x16x64_i8 v[30:33], v[158:161], v[186:189], v[30:33]
	v_mfma_i32_16x16x64_i8 v[30:33], v[154:157], v[190:193], v[30:33]
	v_mfma_i32_16x16x64_i8 v[26:29], v[150:153], v[186:189], v[26:29]
	v_mfma_i32_16x16x64_i8 v[26:29], v[146:149], v[190:193], v[26:29]
	v_mfma_i32_16x16x64_i8 v[14:17], v[158:161], v[238:241], v[14:17]
	v_mfma_i32_16x16x64_i8 v[14:17], v[154:157], v[242:245], v[14:17]
	v_mfma_i32_16x16x64_i8 v[10:13], v[150:153], v[238:241], v[10:13]
	v_mfma_i32_16x16x64_i8 v[10:13], v[146:149], v[242:245], v[10:13]
	v_mfma_i32_16x16x64_i8 v[70:73], v[62:65], v[170:173], v[70:73]
	v_mfma_i32_16x16x64_i8 v[70:73], v[58:61], v[174:177], v[70:73]
	v_mfma_i32_16x16x64_i8 v[66:69], v[54:57], v[170:173], v[66:69]
	v_mfma_i32_16x16x64_i8 v[66:69], v[50:53], v[174:177], v[66:69]
	v_mfma_i32_16x16x64_i8 v[38:41], v[62:65], v[178:181], v[38:41]
	v_mfma_i32_16x16x64_i8 v[38:41], v[58:61], v[182:185], v[38:41]
	v_mfma_i32_16x16x64_i8 v[34:37], v[54:57], v[178:181], v[34:37]
	v_mfma_i32_16x16x64_i8 v[34:37], v[50:53], v[182:185], v[34:37]
	s_barrier
	s_setprio 2
	v_mfma_i32_16x16x64_i8 v[22:25], v[62:65], v[186:189], v[22:25]
	v_mfma_i32_16x16x64_i8 v[22:25], v[58:61], v[190:193], v[22:25]
	v_mfma_i32_16x16x64_i8 v[18:21], v[54:57], v[186:189], v[18:21]
	v_mfma_i32_16x16x64_i8 v[18:21], v[50:53], v[190:193], v[18:21]
	v_mfma_i32_16x16x64_i8 v[6:9], v[62:65], v[238:241], v[6:9]
	v_mfma_i32_16x16x64_i8 v[6:9], v[58:61], v[242:245], v[6:9]
	v_mfma_i32_16x16x64_i8 v[2:5], v[54:57], v[238:241], v[2:5]
	v_mfma_i32_16x16x64_i8 v[2:5], v[50:53], v[242:245], v[2:5]
	s_setprio 0
	ds_read_b128 v[50:53], v235
	ds_read_b128 v[54:57], v235 offset:1024
	ds_read_b128 v[58:61], v235 offset:2048
	ds_read_b128 v[62:65], v235 offset:3072
	ds_read_b128 v[146:149], v236
	ds_read_b128 v[150:153], v236 offset:1024
	ds_read_b128 v[154:157], v236 offset:2048
	ds_read_b128 v[158:161], v236 offset:3072
	s_add_u32 s40, s40, 0x80000
	s_addc_u32 s41, s41, 0
	s_mov_b32 m0, s43
	v_lshl_add_u64 v[246:247], s[40:41], 0, v[194:195]
	ds_read_b128 v[170:173], v226 offset:32768
	ds_read_b128 v[174:177], v226 offset:33792
	ds_read_b128 v[178:181], v226 offset:34816
	ds_read_b128 v[182:185], v226 offset:35840
	ds_read_b128 v[186:189], v226 offset:36864
	ds_read_b128 v[190:193], v226 offset:37888
	ds_read_b128 v[238:241], v226 offset:38912
	ds_read_b128 v[242:245], v226 offset:39936
	global_load_lds_dwordx4 v[246:247], off
	v_lshl_add_u64 v[246:247], s[40:41], 0, v[204:205]
	s_mov_b32 m0, s44
	s_nop 0
	global_load_lds_dwordx4 v[246:247], off
	s_waitcnt vmcnt(8)
	s_waitcnt lgkmcnt(0)
	s_barrier
	s_setprio 1
	s_waitcnt lgkmcnt(0)
	v_mfma_i32_16x16x64_i8 v[142:145], v[50:53], v[170:173], v[142:145]
	v_mfma_i32_16x16x64_i8 v[142:145], v[54:57], v[174:177], v[142:145]
	v_mfma_i32_16x16x64_i8 v[138:141], v[58:61], v[170:173], v[138:141]
	v_mfma_i32_16x16x64_i8 v[138:141], v[62:65], v[174:177], v[138:141]
	v_mfma_i32_16x16x64_i8 v[126:129], v[50:53], v[178:181], v[126:129]
	v_mfma_i32_16x16x64_i8 v[126:129], v[54:57], v[182:185], v[126:129]
	v_mfma_i32_16x16x64_i8 v[122:125], v[58:61], v[178:181], v[122:125]
	v_mfma_i32_16x16x64_i8 v[122:125], v[62:65], v[182:185], v[122:125]
	v_mfma_i32_16x16x64_i8 v[110:113], v[50:53], v[186:189], v[110:113]
	v_mfma_i32_16x16x64_i8 v[110:113], v[54:57], v[190:193], v[110:113]
	v_mfma_i32_16x16x64_i8 v[106:109], v[58:61], v[186:189], v[106:109]
	v_mfma_i32_16x16x64_i8 v[106:109], v[62:65], v[190:193], v[106:109]
	v_mfma_i32_16x16x64_i8 v[94:97], v[50:53], v[238:241], v[94:97]
	v_mfma_i32_16x16x64_i8 v[94:97], v[54:57], v[242:245], v[94:97]
	v_mfma_i32_16x16x64_i8 v[90:93], v[58:61], v[238:241], v[90:93]
	v_mfma_i32_16x16x64_i8 v[90:93], v[62:65], v[242:245], v[90:93]
	v_mfma_i32_16x16x64_i8 v[134:137], v[146:149], v[170:173], v[134:137]
	v_mfma_i32_16x16x64_i8 v[134:137], v[150:153], v[174:177], v[134:137]
	v_mfma_i32_16x16x64_i8 v[130:133], v[154:157], v[170:173], v[130:133]
	v_mfma_i32_16x16x64_i8 v[130:133], v[158:161], v[174:177], v[130:133]
	v_mfma_i32_16x16x64_i8 v[118:121], v[146:149], v[178:181], v[118:121]
	v_mfma_i32_16x16x64_i8 v[118:121], v[150:153], v[182:185], v[118:121]
	v_mfma_i32_16x16x64_i8 v[114:117], v[154:157], v[178:181], v[114:117]
	v_mfma_i32_16x16x64_i8 v[114:117], v[158:161], v[182:185], v[114:117]
	s_barrier
	s_setprio 2
	v_mfma_i32_16x16x64_i8 v[102:105], v[146:149], v[186:189], v[102:105]
	ds_read_b128 v[170:173], v226 offset:49152
	ds_read_b128 v[174:177], v226 offset:50176
	ds_read_b128 v[178:181], v226 offset:51200
	ds_read_b128 v[182:185], v226 offset:52224
	v_mfma_i32_16x16x64_i8 v[102:105], v[150:153], v[190:193], v[102:105]
	v_mfma_i32_16x16x64_i8 v[98:101], v[154:157], v[186:189], v[98:101]
	v_mfma_i32_16x16x64_i8 v[98:101], v[158:161], v[190:193], v[98:101]
	v_mfma_i32_16x16x64_i8 v[86:89], v[146:149], v[238:241], v[86:89]
	ds_read_b128 v[186:189], v226 offset:53248
	v_mfma_i32_16x16x64_i8 v[86:89], v[150:153], v[242:245], v[86:89]
	ds_read_b128 v[190:193], v226 offset:54272
	v_mfma_i32_16x16x64_i8 v[82:85], v[154:157], v[238:241], v[82:85]
	v_mfma_i32_16x16x64_i8 v[82:85], v[158:161], v[242:245], v[82:85]
	s_setprio 0
	s_mov_b32 m0, s72
	v_lshl_add_u64 v[162:163], v[162:163], 0, s[6:7]
	s_add_u32 s36, s36, 0x80080
	ds_read_b128 v[238:241], v226 offset:55296
	ds_read_b128 v[242:245], v226 offset:56320
	global_load_lds_dwordx4 v[162:163], off
	v_lshl_add_u64 v[162:163], v[164:165], 0, s[6:7]
	s_mov_b32 m0, s73
	s_addc_u32 s37, s37, 0
	global_load_lds_dwordx4 v[162:163], off
	v_lshl_add_u64 v[162:163], s[36:37], 0, v[202:203]
	s_mov_b32 m0, s74
	s_nop 0
	global_load_lds_dwordx4 v[162:163], off
	v_lshl_add_u64 v[162:163], s[36:37], 0, v[206:207]
	s_mov_b32 m0, s75
	s_nop 0
	global_load_lds_dwordx4 v[162:163], off
	v_lshl_add_u64 v[162:163], v[166:167], 0, s[6:7]
	s_mov_b32 m0, s51
	s_nop 0
	global_load_lds_dwordx4 v[162:163], off
	v_lshl_add_u64 v[162:163], v[168:169], 0, s[6:7]
	s_mov_b32 m0, s53
	s_nop 0
	global_load_lds_dwordx4 v[162:163], off
	s_waitcnt vmcnt(8)
	s_waitcnt lgkmcnt(0)
	s_barrier
	s_setprio 1
	s_waitcnt lgkmcnt(0)
	v_mfma_i32_16x16x64_i8 v[78:81], v[50:53], v[170:173], v[78:81]
	v_mfma_i32_16x16x64_i8 v[78:81], v[54:57], v[174:177], v[78:81]
	v_mfma_i32_16x16x64_i8 v[74:77], v[58:61], v[170:173], v[74:77]
	v_mfma_i32_16x16x64_i8 v[74:77], v[62:65], v[174:177], v[74:77]
	v_mfma_i32_16x16x64_i8 v[46:49], v[50:53], v[178:181], v[46:49]
	v_mfma_i32_16x16x64_i8 v[46:49], v[54:57], v[182:185], v[46:49]
	v_mfma_i32_16x16x64_i8 v[42:45], v[58:61], v[178:181], v[42:45]
	v_mfma_i32_16x16x64_i8 v[42:45], v[62:65], v[182:185], v[42:45]
	v_mfma_i32_16x16x64_i8 v[30:33], v[50:53], v[186:189], v[30:33]
	v_mfma_i32_16x16x64_i8 v[30:33], v[54:57], v[190:193], v[30:33]
	v_mfma_i32_16x16x64_i8 v[26:29], v[58:61], v[186:189], v[26:29]
	v_mfma_i32_16x16x64_i8 v[26:29], v[62:65], v[190:193], v[26:29]
	v_mfma_i32_16x16x64_i8 v[14:17], v[50:53], v[238:241], v[14:17]
	v_mfma_i32_16x16x64_i8 v[14:17], v[54:57], v[242:245], v[14:17]
	v_mfma_i32_16x16x64_i8 v[10:13], v[58:61], v[238:241], v[10:13]
	v_mfma_i32_16x16x64_i8 v[10:13], v[62:65], v[242:245], v[10:13]
	v_mfma_i32_16x16x64_i8 v[70:73], v[146:149], v[170:173], v[70:73]
	v_mfma_i32_16x16x64_i8 v[70:73], v[150:153], v[174:177], v[70:73]
	v_mfma_i32_16x16x64_i8 v[66:69], v[154:157], v[170:173], v[66:69]
	v_mfma_i32_16x16x64_i8 v[66:69], v[158:161], v[174:177], v[66:69]
	v_mfma_i32_16x16x64_i8 v[38:41], v[146:149], v[178:181], v[38:41]
	v_mfma_i32_16x16x64_i8 v[38:41], v[150:153], v[182:185], v[38:41]
	v_mfma_i32_16x16x64_i8 v[34:37], v[154:157], v[178:181], v[34:37]
	v_mfma_i32_16x16x64_i8 v[34:37], v[158:161], v[182:185], v[34:37]
	v_mfma_i32_16x16x64_i8 v[22:25], v[146:149], v[186:189], v[22:25]
	v_mfma_i32_16x16x64_i8 v[22:25], v[150:153], v[190:193], v[22:25]
	v_mfma_i32_16x16x64_i8 v[18:21], v[154:157], v[186:189], v[18:21]
	v_mfma_i32_16x16x64_i8 v[18:21], v[158:161], v[190:193], v[18:21]
	s_barrier
	s_setprio 2
	v_mfma_i32_16x16x64_i8 v[6:9], v[146:149], v[238:241], v[6:9]
	v_mfma_i32_16x16x64_i8 v[6:9], v[150:153], v[242:245], v[6:9]
	v_mfma_i32_16x16x64_i8 v[2:5], v[154:157], v[238:241], v[2:5]
	v_mfma_i32_16x16x64_i8 v[2:5], v[158:161], v[242:245], v[2:5]
	s_setprio 0
	s_add_i32 s33, s33, 2
	s_add_u32 s38, s38, 0x100
	s_addc_u32 s39, s39, 0
	s_add_u32 s25, s25, 0x100
	s_addc_u32 s29, s29, 0
	s_cmp_gt_u32 s33, 29
	s_cbranch_scc0 .LBB0_740
	s_nop 15
	s_nop 15
	s_and_b64 vcc, exec, s[8:9]
	s_cbranch_vccz .LBB0_743
	s_barrier

.LBB0_746:
	ds_read_b128 v[158:161], v227
	ds_read_b128 v[154:157], v227 offset:1024
	ds_read_b128 v[150:153], v227 offset:2048
	ds_read_b128 v[146:149], v227 offset:3072
	ds_read_b128 v[142:145], v233
	ds_read_b128 v[138:141], v233 offset:1024
	ds_read_b128 v[134:137], v233 offset:2048
	ds_read_b128 v[130:133], v233 offset:3072
	s_add_u32 s38, s29, s36
	s_addc_u32 s39, s33, s37
	s_add_u32 s38, s38, 0x3d000100
	s_addc_u32 s39, s39, 0
	s_add_u32 s81, s25, s36
	s_addc_u32 s82, s79, s37
	s_cmpk_eq_i32 s36, 0x700
	s_cselect_b32 s41, s1, s39
	s_cselect_b32 s40, s0, s38
	s_cselect_b32 s39, s15, s82
	s_cselect_b32 s38, s14, s81
	s_mov_b32 m0, s66
	v_lshl_add_u64 v[242:243], v[162:163], 0, s[36:37]
	ds_read_b128 v[166:169], v226
	ds_read_b128 v[170:173], v226 offset:1024
	ds_read_b128 v[174:177], v226 offset:2048
	ds_read_b128 v[178:181], v226 offset:3072
	ds_read_b128 v[182:185], v226 offset:4096
	ds_read_b128 v[186:189], v226 offset:5120
	ds_read_b128 v[190:193], v226 offset:6144
	ds_read_b128 v[238:241], v226 offset:7168
	global_load_lds_dwordx4 v[242:243], off
	v_lshl_add_u64 v[242:243], v[164:165], 0, s[36:37]
	s_mov_b32 m0, s67
	s_nop 0
	global_load_lds_dwordx4 v[242:243], off
	s_waitcnt vmcnt(8)
	s_waitcnt lgkmcnt(0)
	s_barrier
	s_setprio 1
	s_waitcnt lgkmcnt(0)
	v_mfma_i32_16x16x64_i8 v[30:33], v[158:161], v[166:169], v[30:33]
	v_mfma_i32_16x16x64_i8 v[30:33], v[154:157], v[170:173], v[30:33]
	v_mfma_i32_16x16x64_i8 v[26:29], v[150:153], v[166:169], v[26:29]
	v_mfma_i32_16x16x64_i8 v[26:29], v[146:149], v[170:173], v[26:29]
	v_mfma_i32_16x16x64_i8 v[46:49], v[158:161], v[174:177], v[46:49]
	v_mfma_i32_16x16x64_i8 v[46:49], v[154:157], v[178:181], v[46:49]
	v_mfma_i32_16x16x64_i8 v[42:45], v[150:153], v[174:177], v[42:45]
	v_mfma_i32_16x16x64_i8 v[42:45], v[146:149], v[178:181], v[42:45]
	v_mfma_i32_16x16x64_i8 v[74:77], v[158:161], v[182:185], v[74:77]
	v_mfma_i32_16x16x64_i8 v[74:77], v[154:157], v[186:189], v[74:77]
	v_mfma_i32_16x16x64_i8 v[70:73], v[150:153], v[182:185], v[70:73]
	v_mfma_i32_16x16x64_i8 v[70:73], v[146:149], v[186:189], v[70:73]
	v_mfma_i32_16x16x64_i8 v[94:97], v[158:161], v[190:193], v[94:97]
	v_mfma_i32_16x16x64_i8 v[94:97], v[154:157], v[238:241], v[94:97]
	v_mfma_i32_16x16x64_i8 v[90:93], v[150:153], v[190:193], v[90:93]
	v_mfma_i32_16x16x64_i8 v[90:93], v[146:149], v[238:241], v[90:93]
	v_mfma_i32_16x16x64_i8 v[38:41], v[142:145], v[166:169], v[38:41]
	v_mfma_i32_16x16x64_i8 v[38:41], v[138:141], v[170:173], v[38:41]
	v_mfma_i32_16x16x64_i8 v[34:37], v[134:137], v[166:169], v[34:37]
	v_mfma_i32_16x16x64_i8 v[34:37], v[130:133], v[170:173], v[34:37]
	v_mfma_i32_16x16x64_i8 v[58:61], v[142:145], v[174:177], v[58:61]
	v_mfma_i32_16x16x64_i8 v[58:61], v[138:141], v[178:181], v[58:61]
	v_mfma_i32_16x16x64_i8 v[54:57], v[134:137], v[174:177], v[54:57]
	v_mfma_i32_16x16x64_i8 v[54:57], v[130:133], v[178:181], v[54:57]
	s_barrier
	s_setprio 2
	v_mfma_i32_16x16x64_i8 v[86:89], v[142:145], v[182:185], v[86:89]
	ds_read_b128 v[174:177], v226 offset:16384
	ds_read_b128 v[178:181], v226 offset:17408
	v_mfma_i32_16x16x64_i8 v[86:89], v[138:141], v[186:189], v[86:89]
	v_mfma_i32_16x16x64_i8 v[82:85], v[134:137], v[182:185], v[82:85]
	v_mfma_i32_16x16x64_i8 v[82:85], v[130:133], v[186:189], v[82:85]
	v_mfma_i32_16x16x64_i8 v[102:105], v[142:145], v[190:193], v[102:105]
	ds_read_b128 v[182:185], v226 offset:18432
	v_mfma_i32_16x16x64_i8 v[102:105], v[138:141], v[238:241], v[102:105]
	ds_read_b128 v[186:189], v226 offset:19456
	v_mfma_i32_16x16x64_i8 v[98:101], v[134:137], v[190:193], v[98:101]
	v_mfma_i32_16x16x64_i8 v[98:101], v[130:133], v[238:241], v[98:101]
	s_setprio 0
	s_mov_b32 m0, s68
	v_lshl_add_u64 v[166:167], s[38:39], 0, v[202:203]
	s_add_u32 s82, s38, 0x80000
	ds_read_b128 v[190:193], v226 offset:20480
	ds_read_b128 v[238:241], v226 offset:21504
	ds_read_b128 v[242:245], v226 offset:22528
	ds_read_b128 v[246:249], v226 offset:23552
	global_load_lds_dwordx4 v[166:167], off
	v_lshl_add_u64 v[168:169], s[38:39], 0, v[206:207]
	s_mov_b32 m0, s69
	s_addc_u32 s83, s39, 0
	global_load_lds_dwordx4 v[168:169], off
	v_lshl_add_u64 v[170:171], s[82:83], 0, v[202:203]
	s_mov_b32 m0, s70
	v_lshl_add_u64 v[172:173], s[40:41], 0, v[204:205]
	global_load_lds_dwordx4 v[170:171], off
	v_lshl_add_u64 v[170:171], s[82:83], 0, v[206:207]
	s_mov_b32 m0, s71
	s_nop 0
	global_load_lds_dwordx4 v[170:171], off
	v_lshl_add_u64 v[170:171], s[40:41], 0, v[194:195]
	s_mov_b32 m0, s23
	s_nop 0
	global_load_lds_dwordx4 v[170:171], off
	s_mov_b32 m0, s42
	s_nop 0
	global_load_lds_dwordx4 v[172:173], off
	s_waitcnt vmcnt(8)
	s_waitcnt lgkmcnt(0)
	s_barrier
	s_setprio 1
	s_waitcnt lgkmcnt(0)
	v_mfma_i32_16x16x64_i8 v[110:113], v[158:161], v[174:177], v[110:113]
	v_mfma_i32_16x16x64_i8 v[110:113], v[154:157], v[178:181], v[110:113]
	v_mfma_i32_16x16x64_i8 v[106:109], v[150:153], v[174:177], v[106:109]
	v_mfma_i32_16x16x64_i8 v[106:109], v[146:149], v[178:181], v[106:109]
	v_mfma_i32_16x16x64_i8 v[126:129], v[158:161], v[182:185], v[126:129]
	v_mfma_i32_16x16x64_i8 v[126:129], v[154:157], v[186:189], v[126:129]
	v_mfma_i32_16x16x64_i8 v[118:121], v[150:153], v[182:185], v[118:121]
	v_mfma_i32_16x16x64_i8 v[118:121], v[146:149], v[186:189], v[118:121]
	v_mfma_i32_16x16x64_i8 v[62:65], v[158:161], v[190:193], v[62:65]
	v_mfma_i32_16x16x64_i8 v[62:65], v[154:157], v[238:241], v[62:65]
	v_mfma_i32_16x16x64_i8 v[50:53], v[150:153], v[190:193], v[50:53]
	v_mfma_i32_16x16x64_i8 v[50:53], v[146:149], v[238:241], v[50:53]
	v_mfma_i32_16x16x64_i8 v[14:17], v[158:161], v[242:245], v[14:17]
	v_mfma_i32_16x16x64_i8 v[14:17], v[154:157], v[246:249], v[14:17]
	v_mfma_i32_16x16x64_i8 v[10:13], v[150:153], v[242:245], v[10:13]
	v_mfma_i32_16x16x64_i8 v[10:13], v[146:149], v[246:249], v[10:13]
	v_mfma_i32_16x16x64_i8 v[122:125], v[142:145], v[174:177], v[122:125]
	v_mfma_i32_16x16x64_i8 v[122:125], v[138:141], v[178:181], v[122:125]
	v_mfma_i32_16x16x64_i8 v[114:117], v[134:137], v[174:177], v[114:117]
	v_mfma_i32_16x16x64_i8 v[114:117], v[130:133], v[178:181], v[114:117]
	v_mfma_i32_16x16x64_i8 v[78:81], v[142:145], v[182:185], v[78:81]
	v_mfma_i32_16x16x64_i8 v[78:81], v[138:141], v[186:189], v[78:81]
	v_mfma_i32_16x16x64_i8 v[66:69], v[134:137], v[182:185], v[66:69]
	v_mfma_i32_16x16x64_i8 v[66:69], v[130:133], v[186:189], v[66:69]
	s_barrier
	s_setprio 2
	v_mfma_i32_16x16x64_i8 v[22:25], v[142:145], v[190:193], v[22:25]
	v_mfma_i32_16x16x64_i8 v[22:25], v[138:141], v[238:241], v[22:25]
	v_mfma_i32_16x16x64_i8 v[18:21], v[134:137], v[190:193], v[18:21]
	v_mfma_i32_16x16x64_i8 v[18:21], v[130:133], v[238:241], v[18:21]
	v_mfma_i32_16x16x64_i8 v[6:9], v[142:145], v[242:245], v[6:9]
	v_mfma_i32_16x16x64_i8 v[6:9], v[138:141], v[246:249], v[6:9]
	v_mfma_i32_16x16x64_i8 v[2:5], v[134:137], v[242:245], v[2:5]
	v_mfma_i32_16x16x64_i8 v[2:5], v[130:133], v[246:249], v[2:5]
	s_setprio 0
	ds_read_b128 v[130:133], v235
	ds_read_b128 v[134:137], v235 offset:1024
	ds_read_b128 v[138:141], v235 offset:2048
	ds_read_b128 v[142:145], v235 offset:3072
	ds_read_b128 v[146:149], v236
	ds_read_b128 v[150:153], v236 offset:1024
	ds_read_b128 v[154:157], v236 offset:2048
	ds_read_b128 v[158:161], v236 offset:3072
	s_add_u32 s40, s40, 0x80000
	s_addc_u32 s41, s41, 0
	s_mov_b32 m0, s43
	v_lshl_add_u64 v[250:251], s[40:41], 0, v[194:195]
	ds_read_b128 v[174:177], v226 offset:32768
	ds_read_b128 v[178:181], v226 offset:33792
	ds_read_b128 v[182:185], v226 offset:34816
	ds_read_b128 v[186:189], v226 offset:35840
	ds_read_b128 v[190:193], v226 offset:36864
	ds_read_b128 v[238:241], v226 offset:37888
	ds_read_b128 v[242:245], v226 offset:38912
	ds_read_b128 v[246:249], v226 offset:39936
	global_load_lds_dwordx4 v[250:251], off
	v_lshl_add_u64 v[250:251], s[40:41], 0, v[204:205]
	s_mov_b32 m0, s44
	s_nop 0
	global_load_lds_dwordx4 v[250:251], off
	s_waitcnt vmcnt(8)
	s_waitcnt lgkmcnt(0)
	s_barrier
	s_setprio 1
	s_waitcnt lgkmcnt(0)
	v_mfma_i32_16x16x64_i8 v[30:33], v[130:133], v[174:177], v[30:33]
	v_mfma_i32_16x16x64_i8 v[30:33], v[134:137], v[178:181], v[30:33]
	v_mfma_i32_16x16x64_i8 v[26:29], v[138:141], v[174:177], v[26:29]
	v_mfma_i32_16x16x64_i8 v[26:29], v[142:145], v[178:181], v[26:29]
	v_mfma_i32_16x16x64_i8 v[46:49], v[130:133], v[182:185], v[46:49]
	v_mfma_i32_16x16x64_i8 v[46:49], v[134:137], v[186:189], v[46:49]
	v_mfma_i32_16x16x64_i8 v[42:45], v[138:141], v[182:185], v[42:45]
	v_mfma_i32_16x16x64_i8 v[42:45], v[142:145], v[186:189], v[42:45]
	v_mfma_i32_16x16x64_i8 v[74:77], v[130:133], v[190:193], v[74:77]
	v_mfma_i32_16x16x64_i8 v[74:77], v[134:137], v[238:241], v[74:77]
	v_mfma_i32_16x16x64_i8 v[70:73], v[138:141], v[190:193], v[70:73]
	v_mfma_i32_16x16x64_i8 v[70:73], v[142:145], v[238:241], v[70:73]
	v_mfma_i32_16x16x64_i8 v[94:97], v[130:133], v[242:245], v[94:97]
	v_mfma_i32_16x16x64_i8 v[94:97], v[134:137], v[246:249], v[94:97]
	v_mfma_i32_16x16x64_i8 v[90:93], v[138:141], v[242:245], v[90:93]
	v_mfma_i32_16x16x64_i8 v[90:93], v[142:145], v[246:249], v[90:93]
	v_mfma_i32_16x16x64_i8 v[38:41], v[146:149], v[174:177], v[38:41]
	v_mfma_i32_16x16x64_i8 v[38:41], v[150:153], v[178:181], v[38:41]
	v_mfma_i32_16x16x64_i8 v[34:37], v[154:157], v[174:177], v[34:37]
	v_mfma_i32_16x16x64_i8 v[34:37], v[158:161], v[178:181], v[34:37]
	v_mfma_i32_16x16x64_i8 v[58:61], v[146:149], v[182:185], v[58:61]
	v_mfma_i32_16x16x64_i8 v[58:61], v[150:153], v[186:189], v[58:61]
	v_mfma_i32_16x16x64_i8 v[54:57], v[154:157], v[182:185], v[54:57]
	v_mfma_i32_16x16x64_i8 v[54:57], v[158:161], v[186:189], v[54:57]
	s_barrier
	s_setprio 2
	v_mfma_i32_16x16x64_i8 v[86:89], v[146:149], v[190:193], v[86:89]
	ds_read_b128 v[174:177], v226 offset:49152
	ds_read_b128 v[178:181], v226 offset:50176
	ds_read_b128 v[182:185], v226 offset:51200
	ds_read_b128 v[186:189], v226 offset:52224
	v_mfma_i32_16x16x64_i8 v[86:89], v[150:153], v[238:241], v[86:89]
	v_mfma_i32_16x16x64_i8 v[82:85], v[154:157], v[190:193], v[82:85]
	v_mfma_i32_16x16x64_i8 v[82:85], v[158:161], v[238:241], v[82:85]
	v_mfma_i32_16x16x64_i8 v[102:105], v[146:149], v[242:245], v[102:105]
	ds_read_b128 v[190:193], v226 offset:53248
	v_mfma_i32_16x16x64_i8 v[102:105], v[150:153], v[246:249], v[102:105]
	ds_read_b128 v[238:241], v226 offset:54272
	v_mfma_i32_16x16x64_i8 v[98:101], v[154:157], v[242:245], v[98:101]
	v_mfma_i32_16x16x64_i8 v[98:101], v[158:161], v[246:249], v[98:101]
	s_setprio 0
	s_mov_b32 m0, s72
	v_lshl_add_u64 v[166:167], v[166:167], 0, s[6:7]
	s_add_u32 s38, s38, 0x80080
	ds_read_b128 v[242:245], v226 offset:55296
	ds_read_b128 v[246:249], v226 offset:56320
	global_load_lds_dwordx4 v[166:167], off
	v_lshl_add_u64 v[166:167], v[168:169], 0, s[6:7]
	s_mov_b32 m0, s73
	s_addc_u32 s39, s39, 0
	global_load_lds_dwordx4 v[166:167], off
	v_lshl_add_u64 v[166:167], s[38:39], 0, v[202:203]
	s_mov_b32 m0, s74
	s_nop 0
	global_load_lds_dwordx4 v[166:167], off
	v_lshl_add_u64 v[166:167], s[38:39], 0, v[206:207]
	s_mov_b32 m0, s75
	s_nop 0
	global_load_lds_dwordx4 v[166:167], off
	v_lshl_add_u64 v[166:167], v[170:171], 0, s[6:7]
	s_mov_b32 m0, s51
	s_nop 0
	global_load_lds_dwordx4 v[166:167], off
	v_lshl_add_u64 v[166:167], v[172:173], 0, s[6:7]
	s_mov_b32 m0, s53
	s_nop 0
	global_load_lds_dwordx4 v[166:167], off
	s_waitcnt vmcnt(8)
	s_waitcnt lgkmcnt(0)
	s_barrier
	s_setprio 1
	s_waitcnt lgkmcnt(0)
	v_mfma_i32_16x16x64_i8 v[110:113], v[130:133], v[174:177], v[110:113]
	v_mfma_i32_16x16x64_i8 v[110:113], v[134:137], v[178:181], v[110:113]
	v_mfma_i32_16x16x64_i8 v[106:109], v[138:141], v[174:177], v[106:109]
	v_mfma_i32_16x16x64_i8 v[106:109], v[142:145], v[178:181], v[106:109]
	v_mfma_i32_16x16x64_i8 v[126:129], v[130:133], v[182:185], v[126:129]
	v_mfma_i32_16x16x64_i8 v[126:129], v[134:137], v[186:189], v[126:129]
	v_mfma_i32_16x16x64_i8 v[118:121], v[138:141], v[182:185], v[118:121]
	v_mfma_i32_16x16x64_i8 v[118:121], v[142:145], v[186:189], v[118:121]
	v_mfma_i32_16x16x64_i8 v[62:65], v[130:133], v[190:193], v[62:65]
	v_mfma_i32_16x16x64_i8 v[62:65], v[134:137], v[238:241], v[62:65]
	v_mfma_i32_16x16x64_i8 v[50:53], v[138:141], v[190:193], v[50:53]
	v_mfma_i32_16x16x64_i8 v[50:53], v[142:145], v[238:241], v[50:53]
	v_mfma_i32_16x16x64_i8 v[14:17], v[130:133], v[242:245], v[14:17]
	v_mfma_i32_16x16x64_i8 v[14:17], v[134:137], v[246:249], v[14:17]
	v_mfma_i32_16x16x64_i8 v[10:13], v[138:141], v[242:245], v[10:13]
	v_mfma_i32_16x16x64_i8 v[10:13], v[142:145], v[246:249], v[10:13]
	v_mfma_i32_16x16x64_i8 v[122:125], v[146:149], v[174:177], v[122:125]
	v_mfma_i32_16x16x64_i8 v[122:125], v[150:153], v[178:181], v[122:125]
	v_mfma_i32_16x16x64_i8 v[114:117], v[154:157], v[174:177], v[114:117]
	v_mfma_i32_16x16x64_i8 v[114:117], v[158:161], v[178:181], v[114:117]
	v_mfma_i32_16x16x64_i8 v[78:81], v[146:149], v[182:185], v[78:81]
	v_mfma_i32_16x16x64_i8 v[78:81], v[150:153], v[186:189], v[78:81]
	v_mfma_i32_16x16x64_i8 v[66:69], v[154:157], v[182:185], v[66:69]
	v_mfma_i32_16x16x64_i8 v[66:69], v[158:161], v[186:189], v[66:69]
	v_mfma_i32_16x16x64_i8 v[22:25], v[146:149], v[190:193], v[22:25]
	v_mfma_i32_16x16x64_i8 v[22:25], v[150:153], v[238:241], v[22:25]
	v_mfma_i32_16x16x64_i8 v[18:21], v[154:157], v[190:193], v[18:21]
	v_mfma_i32_16x16x64_i8 v[18:21], v[158:161], v[238:241], v[18:21]
	s_barrier
	s_setprio 2
	v_mfma_i32_16x16x64_i8 v[6:9], v[146:149], v[242:245], v[6:9]
	v_mfma_i32_16x16x64_i8 v[6:9], v[150:153], v[246:249], v[6:9]
	v_mfma_i32_16x16x64_i8 v[2:5], v[154:157], v[242:245], v[2:5]
	v_mfma_i32_16x16x64_i8 v[2:5], v[158:161], v[246:249], v[2:5]
	s_setprio 0
	s_add_i32 s80, s80, 2
	s_add_u32 s36, s36, 0x100
	s_addc_u32 s37, s37, 0
	s_cmp_gt_u32 s80, 13
	s_cbranch_scc0 .LBB0_746
	s_nop 15
	s_nop 15
	s_and_b64 vcc, exec, s[8:9]
	s_cbranch_vccz .LBB0_749
	s_barrier

.LBB0_752:
	ds_read_b128 v[134:137], v227
	ds_read_b128 v[138:141], v227 offset:1024
	ds_read_b128 v[142:145], v227 offset:2048
	ds_read_b128 v[146:149], v227 offset:3072
	ds_read_b128 v[150:153], v233
	ds_read_b128 v[154:157], v233 offset:1024
	ds_read_b128 v[158:161], v233 offset:2048
	ds_read_b128 v[162:165], v233 offset:3072
	s_add_u32 s30, s29, s2
	s_addc_u32 s31, s33, s3
	s_add_u32 s30, s30, 0x200100
	s_addc_u32 s31, s31, 0
	s_add_u32 s77, s25, s2
	s_addc_u32 s78, s40, s3
	s_cmpk_eq_i32 s2, 0xf00
	s_cselect_b32 s35, s0, s31
	s_cselect_b32 s34, s1, s30
	s_cselect_b32 s31, s14, s78
	s_cselect_b32 s30, s15, s77
	s_mov_b32 m0, s66
	v_lshl_add_u64 v[242:243], v[130:131], 0, s[2:3]
	ds_read_b128 v[166:169], v226
	ds_read_b128 v[170:173], v226 offset:1024
	ds_read_b128 v[174:177], v226 offset:2048
	ds_read_b128 v[178:181], v226 offset:3072
	ds_read_b128 v[182:185], v226 offset:4096
	ds_read_b128 v[186:189], v226 offset:5120
	ds_read_b128 v[190:193], v226 offset:6144
	ds_read_b128 v[238:241], v226 offset:7168
	global_load_lds_dwordx4 v[242:243], off
	v_lshl_add_u64 v[242:243], v[132:133], 0, s[2:3]
	s_mov_b32 m0, s67
	s_nop 0
	global_load_lds_dwordx4 v[242:243], off
	s_waitcnt vmcnt(8)
	s_waitcnt lgkmcnt(0)
	s_barrier
	s_setprio 1
	s_waitcnt lgkmcnt(0)
	v_mfma_f32_16x16x32_bf16 v[26:29], v[134:137], v[166:169], v[26:29]
	v_mfma_f32_16x16x32_bf16 v[30:33], v[142:145], v[166:169], v[30:33]
	v_mfma_f32_16x16x32_bf16 v[42:45], v[134:137], v[174:177], v[42:45]
	v_mfma_f32_16x16x32_bf16 v[46:49], v[142:145], v[174:177], v[46:49]
	v_mfma_f32_16x16x32_bf16 v[70:73], v[134:137], v[182:185], v[70:73]
	v_mfma_f32_16x16x32_bf16 v[74:77], v[142:145], v[182:185], v[74:77]
	v_mfma_f32_16x16x32_bf16 v[90:93], v[134:137], v[190:193], v[90:93]
	v_mfma_f32_16x16x32_bf16 v[94:97], v[142:145], v[190:193], v[94:97]
	v_mfma_f32_16x16x32_bf16 v[26:29], v[138:141], v[170:173], v[26:29]
	v_mfma_f32_16x16x32_bf16 v[30:33], v[146:149], v[170:173], v[30:33]
	v_mfma_f32_16x16x32_bf16 v[42:45], v[138:141], v[178:181], v[42:45]
	v_mfma_f32_16x16x32_bf16 v[46:49], v[146:149], v[178:181], v[46:49]
	v_mfma_f32_16x16x32_bf16 v[70:73], v[138:141], v[186:189], v[70:73]
	v_mfma_f32_16x16x32_bf16 v[74:77], v[146:149], v[186:189], v[74:77]
	v_mfma_f32_16x16x32_bf16 v[90:93], v[138:141], v[238:241], v[90:93]
	v_mfma_f32_16x16x32_bf16 v[94:97], v[146:149], v[238:241], v[94:97]
	v_mfma_f32_16x16x32_bf16 v[34:37], v[150:153], v[166:169], v[34:37]
	v_mfma_f32_16x16x32_bf16 v[38:41], v[158:161], v[166:169], v[38:41]
	v_mfma_f32_16x16x32_bf16 v[54:57], v[150:153], v[174:177], v[54:57]
	v_mfma_f32_16x16x32_bf16 v[58:61], v[158:161], v[174:177], v[58:61]
	v_mfma_f32_16x16x32_bf16 v[82:85], v[150:153], v[182:185], v[82:85]
	v_mfma_f32_16x16x32_bf16 v[86:89], v[158:161], v[182:185], v[86:89]
	v_mfma_f32_16x16x32_bf16 v[98:101], v[150:153], v[190:193], v[98:101]
	v_mfma_f32_16x16x32_bf16 v[102:105], v[158:161], v[190:193], v[102:105]
	s_barrier
	s_setprio 2
	v_mfma_f32_16x16x32_bf16 v[34:37], v[154:157], v[170:173], v[34:37]
	ds_read_b128 v[166:169], v226 offset:16384
	v_mfma_f32_16x16x32_bf16 v[38:41], v[162:165], v[170:173], v[38:41]
	v_mfma_f32_16x16x32_bf16 v[54:57], v[154:157], v[178:181], v[54:57]
	v_mfma_f32_16x16x32_bf16 v[58:61], v[162:165], v[178:181], v[58:61]
	ds_read_b128 v[170:173], v226 offset:17408
	ds_read_b128 v[174:177], v226 offset:18432
	v_mfma_f32_16x16x32_bf16 v[82:85], v[154:157], v[186:189], v[82:85]
	v_mfma_f32_16x16x32_bf16 v[86:89], v[162:165], v[186:189], v[86:89]
	ds_read_b128 v[178:181], v226 offset:19456
	ds_read_b128 v[182:185], v226 offset:20480
	v_mfma_f32_16x16x32_bf16 v[98:101], v[154:157], v[238:241], v[98:101]
	v_mfma_f32_16x16x32_bf16 v[102:105], v[162:165], v[238:241], v[102:105]
	ds_read_b128 v[186:189], v226 offset:21504
	ds_read_b128 v[190:193], v226 offset:22528
	s_setprio 0
	s_mov_b32 m0, s68
	v_lshl_add_u64 v[242:243], s[30:31], 0, v[202:203]
	s_add_u32 s78, s30, 0x80000
	ds_read_b128 v[238:241], v226 offset:23552
	global_load_lds_dwordx4 v[242:243], off
	v_lshl_add_u64 v[244:245], s[30:31], 0, v[206:207]
	s_mov_b32 m0, s69
	s_addc_u32 s79, s31, 0
	global_load_lds_dwordx4 v[244:245], off
	v_lshl_add_u64 v[246:247], s[78:79], 0, v[202:203]
	s_mov_b32 m0, s70
	v_lshl_add_u64 v[248:249], s[34:35], 0, v[204:205]
	global_load_lds_dwordx4 v[246:247], off
	v_lshl_add_u64 v[246:247], s[78:79], 0, v[206:207]
	s_mov_b32 m0, s71
	s_nop 0
	global_load_lds_dwordx4 v[246:247], off
	v_lshl_add_u64 v[246:247], s[34:35], 0, v[194:195]
	s_mov_b32 m0, s23
	s_nop 0
	global_load_lds_dwordx4 v[246:247], off
	s_mov_b32 m0, s42
	s_nop 0
	global_load_lds_dwordx4 v[248:249], off
	s_waitcnt vmcnt(8)
	s_waitcnt lgkmcnt(0)
	s_barrier
	s_setprio 1
	s_waitcnt lgkmcnt(0)
	v_mfma_f32_16x16x32_bf16 v[106:109], v[134:137], v[166:169], v[106:109]
	v_mfma_f32_16x16x32_bf16 v[110:113], v[142:145], v[166:169], v[110:113]
	v_mfma_f32_16x16x32_bf16 v[118:121], v[134:137], v[174:177], v[118:121]
	v_mfma_f32_16x16x32_bf16 v[126:129], v[142:145], v[174:177], v[126:129]
	v_mfma_f32_16x16x32_bf16 v[50:53], v[134:137], v[182:185], v[50:53]
	v_mfma_f32_16x16x32_bf16 v[62:65], v[142:145], v[182:185], v[62:65]
	v_mfma_f32_16x16x32_bf16 v[10:13], v[134:137], v[190:193], v[10:13]
	v_mfma_f32_16x16x32_bf16 v[14:17], v[142:145], v[190:193], v[14:17]
	v_mfma_f32_16x16x32_bf16 v[106:109], v[138:141], v[170:173], v[106:109]
	v_mfma_f32_16x16x32_bf16 v[110:113], v[146:149], v[170:173], v[110:113]
	v_mfma_f32_16x16x32_bf16 v[118:121], v[138:141], v[178:181], v[118:121]
	v_mfma_f32_16x16x32_bf16 v[126:129], v[146:149], v[178:181], v[126:129]
	v_mfma_f32_16x16x32_bf16 v[50:53], v[138:141], v[186:189], v[50:53]
	v_mfma_f32_16x16x32_bf16 v[62:65], v[146:149], v[186:189], v[62:65]
	v_mfma_f32_16x16x32_bf16 v[10:13], v[138:141], v[238:241], v[10:13]
	v_mfma_f32_16x16x32_bf16 v[14:17], v[146:149], v[238:241], v[14:17]
	v_mfma_f32_16x16x32_bf16 v[114:117], v[150:153], v[166:169], v[114:117]
	v_mfma_f32_16x16x32_bf16 v[122:125], v[158:161], v[166:169], v[122:125]
	v_mfma_f32_16x16x32_bf16 v[66:69], v[150:153], v[174:177], v[66:69]
	v_mfma_f32_16x16x32_bf16 v[78:81], v[158:161], v[174:177], v[78:81]
	v_mfma_f32_16x16x32_bf16 v[18:21], v[150:153], v[182:185], v[18:21]
	v_mfma_f32_16x16x32_bf16 v[22:25], v[158:161], v[182:185], v[22:25]
	v_mfma_f32_16x16x32_bf16 v[2:5], v[150:153], v[190:193], v[2:5]
	v_mfma_f32_16x16x32_bf16 v[6:9], v[158:161], v[190:193], v[6:9]
	s_barrier
	s_setprio 2
	v_mfma_f32_16x16x32_bf16 v[114:117], v[154:157], v[170:173], v[114:117]
	ds_read_b128 v[134:137], v235
	ds_read_b128 v[138:141], v235 offset:1024
	ds_read_b128 v[142:145], v235 offset:2048
	ds_read_b128 v[146:149], v235 offset:3072
	ds_read_b128 v[150:153], v236
	v_mfma_f32_16x16x32_bf16 v[122:125], v[162:165], v[170:173], v[122:125]
	v_mfma_f32_16x16x32_bf16 v[66:69], v[154:157], v[178:181], v[66:69]
	v_mfma_f32_16x16x32_bf16 v[78:81], v[162:165], v[178:181], v[78:81]
	v_mfma_f32_16x16x32_bf16 v[18:21], v[154:157], v[186:189], v[18:21]
	v_mfma_f32_16x16x32_bf16 v[22:25], v[162:165], v[186:189], v[22:25]
	v_mfma_f32_16x16x32_bf16 v[2:5], v[154:157], v[238:241], v[2:5]
	v_mfma_f32_16x16x32_bf16 v[6:9], v[162:165], v[238:241], v[6:9]
	s_setprio 0
	ds_read_b128 v[154:157], v236 offset:1024
	ds_read_b128 v[158:161], v236 offset:2048
	ds_read_b128 v[162:165], v236 offset:3072
	s_add_u32 s34, s34, 0x80000
	s_addc_u32 s35, s35, 0
	s_mov_b32 m0, s43
	v_lshl_add_u64 v[250:251], s[34:35], 0, v[194:195]
	ds_read_b128 v[166:169], v226 offset:32768
	ds_read_b128 v[170:173], v226 offset:33792
	ds_read_b128 v[174:177], v226 offset:34816
	ds_read_b128 v[178:181], v226 offset:35840
	ds_read_b128 v[182:185], v226 offset:36864
	ds_read_b128 v[186:189], v226 offset:37888
	ds_read_b128 v[190:193], v226 offset:38912
	ds_read_b128 v[238:241], v226 offset:39936
	global_load_lds_dwordx4 v[250:251], off
	v_lshl_add_u64 v[250:251], s[34:35], 0, v[204:205]
	s_mov_b32 m0, s44
	s_nop 0
	global_load_lds_dwordx4 v[250:251], off
	s_waitcnt vmcnt(8)
	s_waitcnt lgkmcnt(0)
	s_barrier
	s_setprio 1
	s_waitcnt lgkmcnt(0)
	v_mfma_f32_16x16x32_bf16 v[26:29], v[134:137], v[166:169], v[26:29]
	v_mfma_f32_16x16x32_bf16 v[30:33], v[142:145], v[166:169], v[30:33]
	v_mfma_f32_16x16x32_bf16 v[42:45], v[134:137], v[174:177], v[42:45]
	v_mfma_f32_16x16x32_bf16 v[46:49], v[142:145], v[174:177], v[46:49]
	v_mfma_f32_16x16x32_bf16 v[70:73], v[134:137], v[182:185], v[70:73]
	v_mfma_f32_16x16x32_bf16 v[74:77], v[142:145], v[182:185], v[74:77]
	v_mfma_f32_16x16x32_bf16 v[90:93], v[134:137], v[190:193], v[90:93]
	v_mfma_f32_16x16x32_bf16 v[94:97], v[142:145], v[190:193], v[94:97]
	v_mfma_f32_16x16x32_bf16 v[26:29], v[138:141], v[170:173], v[26:29]
	v_mfma_f32_16x16x32_bf16 v[30:33], v[146:149], v[170:173], v[30:33]
	v_mfma_f32_16x16x32_bf16 v[42:45], v[138:141], v[178:181], v[42:45]
	v_mfma_f32_16x16x32_bf16 v[46:49], v[146:149], v[178:181], v[46:49]
	v_mfma_f32_16x16x32_bf16 v[70:73], v[138:141], v[186:189], v[70:73]
	v_mfma_f32_16x16x32_bf16 v[74:77], v[146:149], v[186:189], v[74:77]
	v_mfma_f32_16x16x32_bf16 v[90:93], v[138:141], v[238:241], v[90:93]
	v_mfma_f32_16x16x32_bf16 v[94:97], v[146:149], v[238:241], v[94:97]
	v_mfma_f32_16x16x32_bf16 v[34:37], v[150:153], v[166:169], v[34:37]
	v_mfma_f32_16x16x32_bf16 v[38:41], v[158:161], v[166:169], v[38:41]
	v_mfma_f32_16x16x32_bf16 v[54:57], v[150:153], v[174:177], v[54:57]
	v_mfma_f32_16x16x32_bf16 v[58:61], v[158:161], v[174:177], v[58:61]
	v_mfma_f32_16x16x32_bf16 v[82:85], v[150:153], v[182:185], v[82:85]
	v_mfma_f32_16x16x32_bf16 v[86:89], v[158:161], v[182:185], v[86:89]
	v_mfma_f32_16x16x32_bf16 v[98:101], v[150:153], v[190:193], v[98:101]
	v_mfma_f32_16x16x32_bf16 v[102:105], v[158:161], v[190:193], v[102:105]
	s_barrier
	s_setprio 2
	v_mfma_f32_16x16x32_bf16 v[34:37], v[154:157], v[170:173], v[34:37]
	ds_read_b128 v[166:169], v226 offset:49152
	v_mfma_f32_16x16x32_bf16 v[38:41], v[162:165], v[170:173], v[38:41]
	v_mfma_f32_16x16x32_bf16 v[54:57], v[154:157], v[178:181], v[54:57]
	v_mfma_f32_16x16x32_bf16 v[58:61], v[162:165], v[178:181], v[58:61]
	ds_read_b128 v[170:173], v226 offset:50176
	ds_read_b128 v[174:177], v226 offset:51200
	v_mfma_f32_16x16x32_bf16 v[82:85], v[154:157], v[186:189], v[82:85]
	v_mfma_f32_16x16x32_bf16 v[86:89], v[162:165], v[186:189], v[86:89]
	ds_read_b128 v[178:181], v226 offset:52224
	ds_read_b128 v[182:185], v226 offset:53248
	v_mfma_f32_16x16x32_bf16 v[98:101], v[154:157], v[238:241], v[98:101]
	v_mfma_f32_16x16x32_bf16 v[102:105], v[162:165], v[238:241], v[102:105]
	ds_read_b128 v[186:189], v226 offset:54272
	ds_read_b128 v[190:193], v226 offset:55296
	s_setprio 0
	s_mov_b32 m0, s72
	v_lshl_add_u64 v[242:243], v[242:243], 0, s[6:7]
	s_add_u32 s30, s30, 0x80080
	ds_read_b128 v[238:241], v226 offset:56320
	global_load_lds_dwordx4 v[242:243], off
	v_lshl_add_u64 v[242:243], v[244:245], 0, s[6:7]
	s_mov_b32 m0, s73
	s_addc_u32 s31, s31, 0
	global_load_lds_dwordx4 v[242:243], off
	v_lshl_add_u64 v[242:243], s[30:31], 0, v[202:203]
	s_mov_b32 m0, s74
	s_nop 0
	global_load_lds_dwordx4 v[242:243], off
	v_lshl_add_u64 v[242:243], s[30:31], 0, v[206:207]
	s_mov_b32 m0, s75
	s_nop 0
	global_load_lds_dwordx4 v[242:243], off
	v_lshl_add_u64 v[242:243], v[246:247], 0, s[6:7]
	s_mov_b32 m0, s51
	s_nop 0
	global_load_lds_dwordx4 v[242:243], off
	v_lshl_add_u64 v[242:243], v[248:249], 0, s[6:7]
	s_mov_b32 m0, s53
	s_nop 0
	global_load_lds_dwordx4 v[242:243], off
	s_waitcnt vmcnt(8)
	s_waitcnt lgkmcnt(0)
	s_barrier
	s_setprio 1
	s_waitcnt lgkmcnt(0)
	v_mfma_f32_16x16x32_bf16 v[106:109], v[134:137], v[166:169], v[106:109]
	v_mfma_f32_16x16x32_bf16 v[110:113], v[142:145], v[166:169], v[110:113]
	v_mfma_f32_16x16x32_bf16 v[118:121], v[134:137], v[174:177], v[118:121]
	v_mfma_f32_16x16x32_bf16 v[126:129], v[142:145], v[174:177], v[126:129]
	v_mfma_f32_16x16x32_bf16 v[50:53], v[134:137], v[182:185], v[50:53]
	v_mfma_f32_16x16x32_bf16 v[62:65], v[142:145], v[182:185], v[62:65]
	v_mfma_f32_16x16x32_bf16 v[10:13], v[134:137], v[190:193], v[10:13]
	v_mfma_f32_16x16x32_bf16 v[14:17], v[142:145], v[190:193], v[14:17]
	v_mfma_f32_16x16x32_bf16 v[106:109], v[138:141], v[170:173], v[106:109]
	v_mfma_f32_16x16x32_bf16 v[110:113], v[146:149], v[170:173], v[110:113]
	v_mfma_f32_16x16x32_bf16 v[118:121], v[138:141], v[178:181], v[118:121]
	v_mfma_f32_16x16x32_bf16 v[126:129], v[146:149], v[178:181], v[126:129]
	v_mfma_f32_16x16x32_bf16 v[50:53], v[138:141], v[186:189], v[50:53]
	v_mfma_f32_16x16x32_bf16 v[62:65], v[146:149], v[186:189], v[62:65]
	v_mfma_f32_16x16x32_bf16 v[10:13], v[138:141], v[238:241], v[10:13]
	v_mfma_f32_16x16x32_bf16 v[14:17], v[146:149], v[238:241], v[14:17]
	v_mfma_f32_16x16x32_bf16 v[114:117], v[150:153], v[166:169], v[114:117]
	v_mfma_f32_16x16x32_bf16 v[122:125], v[158:161], v[166:169], v[122:125]
	v_mfma_f32_16x16x32_bf16 v[66:69], v[150:153], v[174:177], v[66:69]
	v_mfma_f32_16x16x32_bf16 v[78:81], v[158:161], v[174:177], v[78:81]
	v_mfma_f32_16x16x32_bf16 v[18:21], v[150:153], v[182:185], v[18:21]
	v_mfma_f32_16x16x32_bf16 v[22:25], v[158:161], v[182:185], v[22:25]
	v_mfma_f32_16x16x32_bf16 v[2:5], v[150:153], v[190:193], v[2:5]
	v_mfma_f32_16x16x32_bf16 v[6:9], v[158:161], v[190:193], v[6:9]
	v_mfma_f32_16x16x32_bf16 v[114:117], v[154:157], v[170:173], v[114:117]
	v_mfma_f32_16x16x32_bf16 v[122:125], v[162:165], v[170:173], v[122:125]
	v_mfma_f32_16x16x32_bf16 v[66:69], v[154:157], v[178:181], v[66:69]
	v_mfma_f32_16x16x32_bf16 v[78:81], v[162:165], v[178:181], v[78:81]
	s_barrier
	s_setprio 2
	v_mfma_f32_16x16x32_bf16 v[18:21], v[154:157], v[186:189], v[18:21]
	v_mfma_f32_16x16x32_bf16 v[22:25], v[162:165], v[186:189], v[22:25]
	v_mfma_f32_16x16x32_bf16 v[2:5], v[154:157], v[238:241], v[2:5]
	v_mfma_f32_16x16x32_bf16 v[6:9], v[162:165], v[238:241], v[6:9]
	s_setprio 0
	s_add_i32 s41, s41, 2
	s_add_u32 s2, s2, 0x100
	s_addc_u32 s3, s3, 0
	s_cmp_gt_u32 s41, 29
	s_cbranch_scc0 .LBB0_752
	s_and_b64 vcc, exec, s[8:9]
	s_cbranch_vccz .LBB0_755
	s_barrier

.LBB0_817:
	ds_read_b128 v[130:133], v223
	ds_read_b128 v[134:137], v223 offset:1024
	ds_read_b128 v[138:141], v223 offset:2048
	ds_read_b128 v[142:145], v223 offset:3072
	ds_read_b128 v[146:149], v224
	ds_read_b128 v[150:153], v224 offset:1024
	ds_read_b128 v[154:157], v224 offset:2048
	ds_read_b128 v[158:161], v224 offset:3072
	s_add_u32 s6, s4, 0xfff00080
	s_addc_u32 s7, s5, -1
	s_cmp_eq_u32 s14, 60
	s_cselect_b32 s9, s19, s7
	s_cselect_b32 s8, s18, s6
	s_cselect_b32 s7, s79, s1
	s_cselect_b32 s6, s78, s0
	v_lshl_add_u64 v[194:195], s[4:5], 0, v[170:171]
	s_add_i32 m0, s35, 0xc000
	ds_read_b128 v[174:177], v225
	ds_read_b128 v[178:181], v225 offset:1024
	ds_read_b128 v[182:185], v225 offset:2048
	ds_read_b128 v[186:189], v225 offset:3072
	ds_read_b128 v[190:193], v225 offset:4096
	ds_read_b128 v[202:205], v225 offset:5120
	ds_read_b128 v[206:209], v225 offset:6144
	ds_read_b128 v[210:213], v225 offset:7168
	global_load_lds_dwordx4 v[194:195], off
	v_lshl_add_u64 v[194:195], s[4:5], 0, v[172:173]
	s_add_i32 m0, s35, 0xe000
	s_nop 0
	global_load_lds_dwordx4 v[194:195], off
	s_waitcnt vmcnt(8)
	s_waitcnt lgkmcnt(0)
	s_barrier
	s_setprio 1
	s_waitcnt lgkmcnt(0)
	v_mfma_f32_16x16x32_bf16 v[14:17], v[130:133], v[174:177], v[14:17]
	v_mfma_f32_16x16x32_bf16 v[10:13], v[138:141], v[174:177], v[10:13]
	v_mfma_f32_16x16x32_bf16 v[34:37], v[130:133], v[182:185], v[34:37]
	v_mfma_f32_16x16x32_bf16 v[26:29], v[138:141], v[182:185], v[26:29]
	v_mfma_f32_16x16x32_bf16 v[46:49], v[130:133], v[190:193], v[46:49]
	v_mfma_f32_16x16x32_bf16 v[42:45], v[138:141], v[190:193], v[42:45]
	v_mfma_f32_16x16x32_bf16 v[62:65], v[130:133], v[206:209], v[62:65]
	v_mfma_f32_16x16x32_bf16 v[58:61], v[138:141], v[206:209], v[58:61]
	v_mfma_f32_16x16x32_bf16 v[14:17], v[134:137], v[178:181], v[14:17]
	v_mfma_f32_16x16x32_bf16 v[10:13], v[142:145], v[178:181], v[10:13]
	v_mfma_f32_16x16x32_bf16 v[34:37], v[134:137], v[186:189], v[34:37]
	v_mfma_f32_16x16x32_bf16 v[26:29], v[142:145], v[186:189], v[26:29]
	v_mfma_f32_16x16x32_bf16 v[46:49], v[134:137], v[202:205], v[46:49]
	v_mfma_f32_16x16x32_bf16 v[42:45], v[142:145], v[202:205], v[42:45]
	v_mfma_f32_16x16x32_bf16 v[62:65], v[134:137], v[210:213], v[62:65]
	v_mfma_f32_16x16x32_bf16 v[58:61], v[142:145], v[210:213], v[58:61]
	v_mfma_f32_16x16x32_bf16 v[6:9], v[146:149], v[174:177], v[6:9]
	v_mfma_f32_16x16x32_bf16 v[2:5], v[154:157], v[174:177], v[2:5]
	v_mfma_f32_16x16x32_bf16 v[22:25], v[146:149], v[182:185], v[22:25]
	v_mfma_f32_16x16x32_bf16 v[18:21], v[154:157], v[182:185], v[18:21]
	v_mfma_f32_16x16x32_bf16 v[38:41], v[146:149], v[190:193], v[38:41]
	v_mfma_f32_16x16x32_bf16 v[30:33], v[154:157], v[190:193], v[30:33]
	v_mfma_f32_16x16x32_bf16 v[54:57], v[146:149], v[206:209], v[54:57]
	v_mfma_f32_16x16x32_bf16 v[50:53], v[154:157], v[206:209], v[50:53]
	s_barrier
	s_setprio 2
	v_mfma_f32_16x16x32_bf16 v[6:9], v[150:153], v[178:181], v[6:9]
	ds_read_b128 v[174:177], v225 offset:16384
	v_mfma_f32_16x16x32_bf16 v[2:5], v[158:161], v[178:181], v[2:5]
	v_mfma_f32_16x16x32_bf16 v[22:25], v[150:153], v[186:189], v[22:25]
	v_mfma_f32_16x16x32_bf16 v[18:21], v[158:161], v[186:189], v[18:21]
	ds_read_b128 v[178:181], v225 offset:17408
	ds_read_b128 v[182:185], v225 offset:18432
	v_mfma_f32_16x16x32_bf16 v[38:41], v[150:153], v[202:205], v[38:41]
	v_mfma_f32_16x16x32_bf16 v[30:33], v[158:161], v[202:205], v[30:33]
	ds_read_b128 v[186:189], v225 offset:19456
	ds_read_b128 v[190:193], v225 offset:20480
	v_mfma_f32_16x16x32_bf16 v[54:57], v[150:153], v[210:213], v[54:57]
	v_mfma_f32_16x16x32_bf16 v[50:53], v[158:161], v[210:213], v[50:53]
	ds_read_b128 v[202:205], v225 offset:21504
	ds_read_b128 v[206:209], v225 offset:22528
	s_setprio 0
	s_add_i32 s15, s17, s33
	v_lshl_add_u64 v[194:195], s[6:7], 0, v[164:165]
	s_mov_b32 m0, s15
	ds_read_b128 v[210:213], v225 offset:23552
	global_load_lds_dwordx4 v[194:195], off
	s_add_i32 m0, s15, 0x2000
	s_add_u32 s44, s6, 0x100000
	v_lshl_add_u64 v[214:215], s[6:7], 0, v[168:169]
	s_addc_u32 s45, s7, 0
	s_add_i32 s15, s55, s33
	global_load_lds_dwordx4 v[214:215], off
	v_lshl_add_u64 v[216:217], s[44:45], 0, v[164:165]
	s_mov_b32 m0, s15
	v_lshl_add_u64 v[218:219], s[8:9], 0, v[166:167]
	global_load_lds_dwordx4 v[216:217], off
	v_lshl_add_u64 v[216:217], s[44:45], 0, v[168:169]
	s_add_i32 m0, s15, 0x2000
	s_nop 0
	global_load_lds_dwordx4 v[216:217], off
	v_lshl_add_u64 v[216:217], s[8:9], 0, v[162:163]
	s_mov_b32 m0, s35
	s_nop 0
	global_load_lds_dwordx4 v[216:217], off
	s_mov_b32 m0, s80
	s_nop 0
	global_load_lds_dwordx4 v[218:219], off
	s_waitcnt vmcnt(8)
	s_waitcnt lgkmcnt(0)
	s_barrier
	s_setprio 1
	s_waitcnt lgkmcnt(0)
	v_mfma_f32_16x16x32_bf16 v[78:81], v[130:133], v[174:177], v[78:81]
	v_mfma_f32_16x16x32_bf16 v[74:77], v[138:141], v[174:177], v[74:77]
	v_mfma_f32_16x16x32_bf16 v[94:97], v[130:133], v[182:185], v[94:97]
	v_mfma_f32_16x16x32_bf16 v[90:93], v[138:141], v[182:185], v[90:93]
	v_mfma_f32_16x16x32_bf16 v[110:113], v[130:133], v[190:193], v[110:113]
	v_mfma_f32_16x16x32_bf16 v[106:109], v[138:141], v[190:193], v[106:109]
	v_mfma_f32_16x16x32_bf16 v[118:121], v[130:133], v[206:209], v[118:121]
	v_mfma_f32_16x16x32_bf16 v[114:117], v[138:141], v[206:209], v[114:117]
	v_mfma_f32_16x16x32_bf16 v[78:81], v[134:137], v[178:181], v[78:81]
	v_mfma_f32_16x16x32_bf16 v[74:77], v[142:145], v[178:181], v[74:77]
	v_mfma_f32_16x16x32_bf16 v[94:97], v[134:137], v[186:189], v[94:97]
	v_mfma_f32_16x16x32_bf16 v[90:93], v[142:145], v[186:189], v[90:93]
	v_mfma_f32_16x16x32_bf16 v[110:113], v[134:137], v[202:205], v[110:113]
	v_mfma_f32_16x16x32_bf16 v[106:109], v[142:145], v[202:205], v[106:109]
	v_mfma_f32_16x16x32_bf16 v[118:121], v[134:137], v[210:213], v[118:121]
	v_mfma_f32_16x16x32_bf16 v[114:117], v[142:145], v[210:213], v[114:117]
	v_mfma_f32_16x16x32_bf16 v[70:73], v[146:149], v[174:177], v[70:73]
	v_mfma_f32_16x16x32_bf16 v[66:69], v[154:157], v[174:177], v[66:69]
	v_mfma_f32_16x16x32_bf16 v[86:89], v[146:149], v[182:185], v[86:89]
	v_mfma_f32_16x16x32_bf16 v[82:85], v[154:157], v[182:185], v[82:85]
	v_mfma_f32_16x16x32_bf16 v[102:105], v[146:149], v[190:193], v[102:105]
	v_mfma_f32_16x16x32_bf16 v[98:101], v[154:157], v[190:193], v[98:101]
	v_mfma_f32_16x16x32_bf16 v[122:125], v[146:149], v[206:209], v[122:125]
	v_mfma_f32_16x16x32_bf16 v[126:129], v[154:157], v[206:209], v[126:129]
	s_barrier
	s_setprio 2
	v_mfma_f32_16x16x32_bf16 v[70:73], v[150:153], v[178:181], v[70:73]
	v_mfma_f32_16x16x32_bf16 v[66:69], v[158:161], v[178:181], v[66:69]
	v_mfma_f32_16x16x32_bf16 v[86:89], v[150:153], v[186:189], v[86:89]
	v_mfma_f32_16x16x32_bf16 v[82:85], v[158:161], v[186:189], v[82:85]
	v_mfma_f32_16x16x32_bf16 v[102:105], v[150:153], v[202:205], v[102:105]
	v_mfma_f32_16x16x32_bf16 v[98:101], v[158:161], v[202:205], v[98:101]
	v_mfma_f32_16x16x32_bf16 v[122:125], v[150:153], v[210:213], v[122:125]
	v_mfma_f32_16x16x32_bf16 v[126:129], v[158:161], v[210:213], v[126:129]
	s_setprio 0
	s_add_i32 s56, 0, 0x18000
	s_add_i32 s57, 0, 0x1c000
	v_add_u32_e32 v142, s56, v222
	v_add_u32_e32 v158, s57, v222
	ds_read_b128 v[130:133], v142
	ds_read_b128 v[134:137], v142 offset:1024
	ds_read_b128 v[138:141], v142 offset:2048
	ds_read_b128 v[142:145], v142 offset:3072
	ds_read_b128 v[146:149], v158
	ds_read_b128 v[150:153], v158 offset:1024
	ds_read_b128 v[154:157], v158 offset:2048
	ds_read_b128 v[158:161], v158 offset:3072
	s_add_u32 s8, s8, 0x100000
	s_addc_u32 s9, s9, 0
	s_mov_b32 m0, s59
	v_lshl_add_u64 v[238:239], s[8:9], 0, v[162:163]
	ds_read_b128 v[174:177], v225 offset:32768
	ds_read_b128 v[178:181], v225 offset:33792
	ds_read_b128 v[182:185], v225 offset:34816
	ds_read_b128 v[186:189], v225 offset:35840
	ds_read_b128 v[190:193], v225 offset:36864
	ds_read_b128 v[202:205], v225 offset:37888
	ds_read_b128 v[206:209], v225 offset:38912
	ds_read_b128 v[210:213], v225 offset:39936
	global_load_lds_dwordx4 v[238:239], off
	v_lshl_add_u64 v[238:239], s[8:9], 0, v[166:167]
	s_mov_b32 m0, s60
	s_nop 0
	global_load_lds_dwordx4 v[238:239], off
	s_waitcnt vmcnt(8)
	s_waitcnt lgkmcnt(0)
	s_barrier
	s_setprio 1
	s_waitcnt lgkmcnt(0)
	v_mfma_f32_16x16x32_bf16 v[14:17], v[130:133], v[174:177], v[14:17]
	v_mfma_f32_16x16x32_bf16 v[10:13], v[138:141], v[174:177], v[10:13]
	v_mfma_f32_16x16x32_bf16 v[34:37], v[130:133], v[182:185], v[34:37]
	v_mfma_f32_16x16x32_bf16 v[26:29], v[138:141], v[182:185], v[26:29]
	v_mfma_f32_16x16x32_bf16 v[46:49], v[130:133], v[190:193], v[46:49]
	v_mfma_f32_16x16x32_bf16 v[42:45], v[138:141], v[190:193], v[42:45]
	v_mfma_f32_16x16x32_bf16 v[62:65], v[130:133], v[206:209], v[62:65]
	v_mfma_f32_16x16x32_bf16 v[58:61], v[138:141], v[206:209], v[58:61]
	v_mfma_f32_16x16x32_bf16 v[14:17], v[134:137], v[178:181], v[14:17]
	v_mfma_f32_16x16x32_bf16 v[10:13], v[142:145], v[178:181], v[10:13]
	v_mfma_f32_16x16x32_bf16 v[34:37], v[134:137], v[186:189], v[34:37]
	v_mfma_f32_16x16x32_bf16 v[26:29], v[142:145], v[186:189], v[26:29]
	v_mfma_f32_16x16x32_bf16 v[46:49], v[134:137], v[202:205], v[46:49]
	v_mfma_f32_16x16x32_bf16 v[42:45], v[142:145], v[202:205], v[42:45]
	v_mfma_f32_16x16x32_bf16 v[62:65], v[134:137], v[210:213], v[62:65]
	v_mfma_f32_16x16x32_bf16 v[58:61], v[142:145], v[210:213], v[58:61]
	v_mfma_f32_16x16x32_bf16 v[6:9], v[146:149], v[174:177], v[6:9]
	v_mfma_f32_16x16x32_bf16 v[2:5], v[154:157], v[174:177], v[2:5]
	v_mfma_f32_16x16x32_bf16 v[22:25], v[146:149], v[182:185], v[22:25]
	v_mfma_f32_16x16x32_bf16 v[18:21], v[154:157], v[182:185], v[18:21]
	v_mfma_f32_16x16x32_bf16 v[38:41], v[146:149], v[190:193], v[38:41]
	v_mfma_f32_16x16x32_bf16 v[30:33], v[154:157], v[190:193], v[30:33]
	v_mfma_f32_16x16x32_bf16 v[54:57], v[146:149], v[206:209], v[54:57]
	v_mfma_f32_16x16x32_bf16 v[50:53], v[154:157], v[206:209], v[50:53]
	s_barrier
	s_setprio 2
	v_mfma_f32_16x16x32_bf16 v[6:9], v[150:153], v[178:181], v[6:9]
	ds_read_b128 v[174:177], v225 offset:49152
	v_mfma_f32_16x16x32_bf16 v[2:5], v[158:161], v[178:181], v[2:5]
	v_mfma_f32_16x16x32_bf16 v[22:25], v[150:153], v[186:189], v[22:25]
	v_mfma_f32_16x16x32_bf16 v[18:21], v[158:161], v[186:189], v[18:21]
	ds_read_b128 v[178:181], v225 offset:50176
	ds_read_b128 v[182:185], v225 offset:51200
	v_mfma_f32_16x16x32_bf16 v[38:41], v[150:153], v[202:205], v[38:41]
	v_mfma_f32_16x16x32_bf16 v[30:33], v[158:161], v[202:205], v[30:33]
	ds_read_b128 v[186:189], v225 offset:52224
	ds_read_b128 v[190:193], v225 offset:53248
	v_mfma_f32_16x16x32_bf16 v[54:57], v[150:153], v[210:213], v[54:57]
	v_mfma_f32_16x16x32_bf16 v[50:53], v[158:161], v[210:213], v[50:53]
	ds_read_b128 v[202:205], v225 offset:54272
	ds_read_b128 v[206:209], v225 offset:55296
	s_setprio 0
	s_add_i32 s8, s56, s33
	v_lshl_add_u64 v[194:195], v[194:195], 0, s[26:27]
	s_mov_b32 m0, s8
	ds_read_b128 v[210:213], v225 offset:56320
	global_load_lds_dwordx4 v[194:195], off
	s_add_i32 m0, s8, 0x2000
	s_add_u32 s6, s6, 0x100080
	v_lshl_add_u64 v[194:195], v[214:215], 0, s[26:27]
	s_addc_u32 s7, s7, 0
	s_add_i32 s8, s57, s33
	global_load_lds_dwordx4 v[194:195], off
	v_lshl_add_u64 v[194:195], s[6:7], 0, v[164:165]
	s_mov_b32 m0, s8
	s_nop 0
	global_load_lds_dwordx4 v[194:195], off
	v_lshl_add_u64 v[194:195], s[6:7], 0, v[168:169]
	s_add_i32 m0, s8, 0x2000
	s_nop 0
	global_load_lds_dwordx4 v[194:195], off
	v_lshl_add_u64 v[194:195], v[216:217], 0, s[26:27]
	s_mov_b32 m0, s65
	s_nop 0
	global_load_lds_dwordx4 v[194:195], off
	v_lshl_add_u64 v[194:195], v[218:219], 0, s[26:27]
	s_mov_b32 m0, s66
	s_nop 0
	global_load_lds_dwordx4 v[194:195], off
	s_waitcnt vmcnt(8)
	s_waitcnt lgkmcnt(0)
	s_barrier
	s_setprio 1
	s_waitcnt lgkmcnt(0)
	v_mfma_f32_16x16x32_bf16 v[78:81], v[130:133], v[174:177], v[78:81]
	v_mfma_f32_16x16x32_bf16 v[74:77], v[138:141], v[174:177], v[74:77]
	v_mfma_f32_16x16x32_bf16 v[94:97], v[130:133], v[182:185], v[94:97]
	v_mfma_f32_16x16x32_bf16 v[90:93], v[138:141], v[182:185], v[90:93]
	v_mfma_f32_16x16x32_bf16 v[110:113], v[130:133], v[190:193], v[110:113]
	v_mfma_f32_16x16x32_bf16 v[106:109], v[138:141], v[190:193], v[106:109]
	v_mfma_f32_16x16x32_bf16 v[118:121], v[130:133], v[206:209], v[118:121]
	v_mfma_f32_16x16x32_bf16 v[114:117], v[138:141], v[206:209], v[114:117]
	v_mfma_f32_16x16x32_bf16 v[78:81], v[134:137], v[178:181], v[78:81]
	v_mfma_f32_16x16x32_bf16 v[74:77], v[142:145], v[178:181], v[74:77]
	v_mfma_f32_16x16x32_bf16 v[94:97], v[134:137], v[186:189], v[94:97]
	v_mfma_f32_16x16x32_bf16 v[90:93], v[142:145], v[186:189], v[90:93]
	v_mfma_f32_16x16x32_bf16 v[110:113], v[134:137], v[202:205], v[110:113]
	v_mfma_f32_16x16x32_bf16 v[106:109], v[142:145], v[202:205], v[106:109]
	v_mfma_f32_16x16x32_bf16 v[118:121], v[134:137], v[210:213], v[118:121]
	v_mfma_f32_16x16x32_bf16 v[114:117], v[142:145], v[210:213], v[114:117]
	v_mfma_f32_16x16x32_bf16 v[70:73], v[146:149], v[174:177], v[70:73]
	v_mfma_f32_16x16x32_bf16 v[66:69], v[154:157], v[174:177], v[66:69]
	v_mfma_f32_16x16x32_bf16 v[86:89], v[146:149], v[182:185], v[86:89]
	v_mfma_f32_16x16x32_bf16 v[82:85], v[154:157], v[182:185], v[82:85]
	v_mfma_f32_16x16x32_bf16 v[102:105], v[146:149], v[190:193], v[102:105]
	v_mfma_f32_16x16x32_bf16 v[98:101], v[154:157], v[190:193], v[98:101]
	v_mfma_f32_16x16x32_bf16 v[122:125], v[146:149], v[206:209], v[122:125]
	v_mfma_f32_16x16x32_bf16 v[126:129], v[154:157], v[206:209], v[126:129]
	v_mfma_f32_16x16x32_bf16 v[70:73], v[150:153], v[178:181], v[70:73]
	v_mfma_f32_16x16x32_bf16 v[66:69], v[158:161], v[178:181], v[66:69]
	v_mfma_f32_16x16x32_bf16 v[86:89], v[150:153], v[186:189], v[86:89]
	v_mfma_f32_16x16x32_bf16 v[82:85], v[158:161], v[186:189], v[82:85]
	s_barrier
	s_setprio 2
	v_mfma_f32_16x16x32_bf16 v[102:105], v[150:153], v[202:205], v[102:105]
	v_mfma_f32_16x16x32_bf16 v[98:101], v[158:161], v[202:205], v[98:101]
	v_mfma_f32_16x16x32_bf16 v[122:125], v[150:153], v[210:213], v[122:125]
	v_mfma_f32_16x16x32_bf16 v[126:129], v[158:161], v[210:213], v[126:129]
	s_setprio 0
	s_add_i32 s14, s14, 2
	s_add_u32 s4, s4, 0x100
	s_addc_u32 s5, s5, 0
	s_add_u32 s0, s0, 0x100
	s_addc_u32 s1, s1, 0
	s_cmp_gt_u32 s14, 61
	s_cbranch_scc0 .LBB0_817
	s_and_b64 vcc, exec, s[28:29]
	s_cbranch_vccz .LBB0_820
	s_barrier

.LBB0_961:
	ds_read_b128 v[158:161], v185
	ds_read_b128 v[154:157], v185 offset:1024
	ds_read_b128 v[150:153], v185 offset:2048
	ds_read_b128 v[146:149], v185 offset:3072
	ds_read_b128 v[142:145], v186
	ds_read_b128 v[138:141], v186 offset:1024
	ds_read_b128 v[134:137], v186 offset:2048
	ds_read_b128 v[130:133], v186 offset:3072
	s_add_u32 s30, s28, 0xfff80080
	s_addc_u32 s31, s29, -1
	s_cmp_eq_u32 s45, 28
	s_cselect_b32 s35, s1, s31
	s_cselect_b32 s34, s15, s30
	s_cselect_b32 s31, s19, s44
	s_cselect_b32 s30, s42, s43
	v_lshl_add_u64 v[220:221], s[28:29], 0, v[170:171]
	s_add_i32 m0, s27, 0xc000
	ds_read_b128 v[174:177], v187
	ds_read_b128 v[178:181], v187 offset:1024
	ds_read_b128 v[188:191], v187 offset:2048
	ds_read_b128 v[192:195], v187 offset:3072
	ds_read_b128 v[202:205], v187 offset:4096
	ds_read_b128 v[206:209], v187 offset:5120
	ds_read_b128 v[210:213], v187 offset:6144
	ds_read_b128 v[214:217], v187 offset:7168
	global_load_lds_dwordx4 v[220:221], off
	v_lshl_add_u64 v[220:221], s[28:29], 0, v[172:173]
	s_add_i32 m0, s27, 0xe000
	s_nop 0
	global_load_lds_dwordx4 v[220:221], off
	s_waitcnt vmcnt(8)
	s_waitcnt lgkmcnt(0)
	s_barrier
	s_setprio 1
	s_waitcnt lgkmcnt(0)
	v_mfma_i32_16x16x64_i8 v[126:129], v[158:161], v[174:177], v[126:129]
	v_mfma_i32_16x16x64_i8 v[126:129], v[154:157], v[178:181], v[126:129]
	v_mfma_i32_16x16x64_i8 v[122:125], v[150:153], v[174:177], v[122:125]
	v_mfma_i32_16x16x64_i8 v[122:125], v[146:149], v[178:181], v[122:125]
	v_mfma_i32_16x16x64_i8 v[110:113], v[158:161], v[188:191], v[110:113]
	v_mfma_i32_16x16x64_i8 v[110:113], v[154:157], v[192:195], v[110:113]
	v_mfma_i32_16x16x64_i8 v[106:109], v[150:153], v[188:191], v[106:109]
	v_mfma_i32_16x16x64_i8 v[106:109], v[146:149], v[192:195], v[106:109]
	v_mfma_i32_16x16x64_i8 v[94:97], v[158:161], v[202:205], v[94:97]
	v_mfma_i32_16x16x64_i8 v[94:97], v[154:157], v[206:209], v[94:97]
	v_mfma_i32_16x16x64_i8 v[90:93], v[150:153], v[202:205], v[90:93]
	v_mfma_i32_16x16x64_i8 v[90:93], v[146:149], v[206:209], v[90:93]
	v_mfma_i32_16x16x64_i8 v[78:81], v[158:161], v[210:213], v[78:81]
	v_mfma_i32_16x16x64_i8 v[78:81], v[154:157], v[214:217], v[78:81]
	v_mfma_i32_16x16x64_i8 v[74:77], v[150:153], v[210:213], v[74:77]
	v_mfma_i32_16x16x64_i8 v[74:77], v[146:149], v[214:217], v[74:77]
	v_mfma_i32_16x16x64_i8 v[118:121], v[142:145], v[174:177], v[118:121]
	v_mfma_i32_16x16x64_i8 v[118:121], v[138:141], v[178:181], v[118:121]
	v_mfma_i32_16x16x64_i8 v[114:117], v[134:137], v[174:177], v[114:117]
	v_mfma_i32_16x16x64_i8 v[114:117], v[130:133], v[178:181], v[114:117]
	v_mfma_i32_16x16x64_i8 v[102:105], v[142:145], v[188:191], v[102:105]
	v_mfma_i32_16x16x64_i8 v[102:105], v[138:141], v[192:195], v[102:105]
	v_mfma_i32_16x16x64_i8 v[98:101], v[134:137], v[188:191], v[98:101]
	v_mfma_i32_16x16x64_i8 v[98:101], v[130:133], v[192:195], v[98:101]
	s_barrier
	s_setprio 2
	v_mfma_i32_16x16x64_i8 v[86:89], v[142:145], v[202:205], v[86:89]
	ds_read_b128 v[188:191], v187 offset:16384
	ds_read_b128 v[192:195], v187 offset:17408
	v_mfma_i32_16x16x64_i8 v[86:89], v[138:141], v[206:209], v[86:89]
	v_mfma_i32_16x16x64_i8 v[82:85], v[134:137], v[202:205], v[82:85]
	v_mfma_i32_16x16x64_i8 v[82:85], v[130:133], v[206:209], v[82:85]
	v_mfma_i32_16x16x64_i8 v[70:73], v[142:145], v[210:213], v[70:73]
	ds_read_b128 v[202:205], v187 offset:18432
	v_mfma_i32_16x16x64_i8 v[70:73], v[138:141], v[214:217], v[70:73]
	ds_read_b128 v[206:209], v187 offset:19456
	v_mfma_i32_16x16x64_i8 v[66:69], v[134:137], v[210:213], v[66:69]
	v_mfma_i32_16x16x64_i8 v[66:69], v[130:133], v[214:217], v[66:69]
	s_setprio 0
	s_add_i32 s46, s17, s9
	v_lshl_add_u64 v[174:175], s[30:31], 0, v[166:167]
	s_mov_b32 m0, s46
	ds_read_b128 v[210:213], v187 offset:20480
	ds_read_b128 v[214:217], v187 offset:21504
	ds_read_b128 v[220:223], v187 offset:22528
	ds_read_b128 v[224:227], v187 offset:23552
	global_load_lds_dwordx4 v[174:175], off
	s_add_i32 m0, s46, 0x2000
	s_add_u32 s46, s30, 0x80000
	v_lshl_add_u64 v[176:177], s[30:31], 0, v[162:163]
	s_addc_u32 s47, s31, 0
	s_add_i32 s48, s55, s9
	global_load_lds_dwordx4 v[176:177], off
	v_lshl_add_u64 v[178:179], s[46:47], 0, v[166:167]
	s_mov_b32 m0, s48
	v_lshl_add_u64 v[180:181], s[34:35], 0, v[164:165]
	global_load_lds_dwordx4 v[178:179], off
	v_lshl_add_u64 v[178:179], s[46:47], 0, v[162:163]
	s_add_i32 m0, s48, 0x2000
	s_nop 0
	global_load_lds_dwordx4 v[178:179], off
	v_lshl_add_u64 v[178:179], s[34:35], 0, v[168:169]
	s_mov_b32 m0, s27
	s_nop 0
	global_load_lds_dwordx4 v[178:179], off
	s_mov_b32 m0, s33
	s_nop 0
	global_load_lds_dwordx4 v[180:181], off
	s_waitcnt vmcnt(8)
	s_waitcnt lgkmcnt(0)
	s_barrier
	s_setprio 1
	s_waitcnt lgkmcnt(0)
	v_mfma_i32_16x16x64_i8 v[62:65], v[158:161], v[188:191], v[62:65]
	v_mfma_i32_16x16x64_i8 v[62:65], v[154:157], v[192:195], v[62:65]
	v_mfma_i32_16x16x64_i8 v[58:61], v[150:153], v[188:191], v[58:61]
	v_mfma_i32_16x16x64_i8 v[58:61], v[146:149], v[192:195], v[58:61]
	v_mfma_i32_16x16x64_i8 v[46:49], v[158:161], v[202:205], v[46:49]
	v_mfma_i32_16x16x64_i8 v[46:49], v[154:157], v[206:209], v[46:49]
	v_mfma_i32_16x16x64_i8 v[42:45], v[150:153], v[202:205], v[42:45]
	v_mfma_i32_16x16x64_i8 v[42:45], v[146:149], v[206:209], v[42:45]
	v_mfma_i32_16x16x64_i8 v[30:33], v[158:161], v[210:213], v[30:33]
	v_mfma_i32_16x16x64_i8 v[30:33], v[154:157], v[214:217], v[30:33]
	v_mfma_i32_16x16x64_i8 v[26:29], v[150:153], v[210:213], v[26:29]
	v_mfma_i32_16x16x64_i8 v[26:29], v[146:149], v[214:217], v[26:29]
	v_mfma_i32_16x16x64_i8 v[14:17], v[158:161], v[220:223], v[14:17]
	v_mfma_i32_16x16x64_i8 v[14:17], v[154:157], v[224:227], v[14:17]
	v_mfma_i32_16x16x64_i8 v[10:13], v[150:153], v[220:223], v[10:13]
	v_mfma_i32_16x16x64_i8 v[10:13], v[146:149], v[224:227], v[10:13]
	v_mfma_i32_16x16x64_i8 v[54:57], v[142:145], v[188:191], v[54:57]
	v_mfma_i32_16x16x64_i8 v[54:57], v[138:141], v[192:195], v[54:57]
	v_mfma_i32_16x16x64_i8 v[50:53], v[134:137], v[188:191], v[50:53]
	v_mfma_i32_16x16x64_i8 v[50:53], v[130:133], v[192:195], v[50:53]
	v_mfma_i32_16x16x64_i8 v[38:41], v[142:145], v[202:205], v[38:41]
	v_mfma_i32_16x16x64_i8 v[38:41], v[138:141], v[206:209], v[38:41]
	v_mfma_i32_16x16x64_i8 v[34:37], v[134:137], v[202:205], v[34:37]
	v_mfma_i32_16x16x64_i8 v[34:37], v[130:133], v[206:209], v[34:37]
	s_barrier
	s_setprio 2
	v_mfma_i32_16x16x64_i8 v[22:25], v[142:145], v[210:213], v[22:25]
	v_mfma_i32_16x16x64_i8 v[22:25], v[138:141], v[214:217], v[22:25]
	v_mfma_i32_16x16x64_i8 v[18:21], v[134:137], v[210:213], v[18:21]
	v_mfma_i32_16x16x64_i8 v[18:21], v[130:133], v[214:217], v[18:21]
	v_mfma_i32_16x16x64_i8 v[6:9], v[142:145], v[220:223], v[6:9]
	v_mfma_i32_16x16x64_i8 v[6:9], v[138:141], v[224:227], v[6:9]
	v_mfma_i32_16x16x64_i8 v[2:5], v[134:137], v[220:223], v[2:5]
	v_mfma_i32_16x16x64_i8 v[2:5], v[130:133], v[224:227], v[2:5]
	s_setprio 0
	v_add_u32_e32 v142, s56, v183
	v_add_u32_e32 v158, s57, v183
	ds_read_b128 v[130:133], v142
	ds_read_b128 v[134:137], v142 offset:1024
	ds_read_b128 v[138:141], v142 offset:2048
	ds_read_b128 v[142:145], v142 offset:3072
	ds_read_b128 v[146:149], v158
	ds_read_b128 v[150:153], v158 offset:1024
	ds_read_b128 v[154:157], v158 offset:2048
	ds_read_b128 v[158:161], v158 offset:3072
	s_add_u32 s34, s34, 0x80000
	s_addc_u32 s35, s35, 0
	s_mov_b32 m0, s36
	v_lshl_add_u64 v[232:233], s[34:35], 0, v[168:169]
	ds_read_b128 v[188:191], v187 offset:32768
	ds_read_b128 v[192:195], v187 offset:33792
	ds_read_b128 v[202:205], v187 offset:34816
	ds_read_b128 v[206:209], v187 offset:35840
	ds_read_b128 v[210:213], v187 offset:36864
	ds_read_b128 v[214:217], v187 offset:37888
	ds_read_b128 v[220:223], v187 offset:38912
	ds_read_b128 v[224:227], v187 offset:39936
	global_load_lds_dwordx4 v[232:233], off
	v_lshl_add_u64 v[232:233], s[34:35], 0, v[164:165]
	s_mov_b32 m0, s37
	s_nop 0
	global_load_lds_dwordx4 v[232:233], off
	s_waitcnt vmcnt(8)
	s_waitcnt lgkmcnt(0)
	s_barrier
	s_setprio 1
	s_waitcnt lgkmcnt(0)
	v_mfma_i32_16x16x64_i8 v[126:129], v[130:133], v[188:191], v[126:129]
	v_mfma_i32_16x16x64_i8 v[126:129], v[134:137], v[192:195], v[126:129]
	v_mfma_i32_16x16x64_i8 v[122:125], v[138:141], v[188:191], v[122:125]
	v_mfma_i32_16x16x64_i8 v[122:125], v[142:145], v[192:195], v[122:125]
	v_mfma_i32_16x16x64_i8 v[110:113], v[130:133], v[202:205], v[110:113]
	v_mfma_i32_16x16x64_i8 v[110:113], v[134:137], v[206:209], v[110:113]
	v_mfma_i32_16x16x64_i8 v[106:109], v[138:141], v[202:205], v[106:109]
	v_mfma_i32_16x16x64_i8 v[106:109], v[142:145], v[206:209], v[106:109]
	v_mfma_i32_16x16x64_i8 v[94:97], v[130:133], v[210:213], v[94:97]
	v_mfma_i32_16x16x64_i8 v[94:97], v[134:137], v[214:217], v[94:97]
	v_mfma_i32_16x16x64_i8 v[90:93], v[138:141], v[210:213], v[90:93]
	v_mfma_i32_16x16x64_i8 v[90:93], v[142:145], v[214:217], v[90:93]
	v_mfma_i32_16x16x64_i8 v[78:81], v[130:133], v[220:223], v[78:81]
	v_mfma_i32_16x16x64_i8 v[78:81], v[134:137], v[224:227], v[78:81]
	v_mfma_i32_16x16x64_i8 v[74:77], v[138:141], v[220:223], v[74:77]
	v_mfma_i32_16x16x64_i8 v[74:77], v[142:145], v[224:227], v[74:77]
	v_mfma_i32_16x16x64_i8 v[118:121], v[146:149], v[188:191], v[118:121]
	v_mfma_i32_16x16x64_i8 v[118:121], v[150:153], v[192:195], v[118:121]
	v_mfma_i32_16x16x64_i8 v[114:117], v[154:157], v[188:191], v[114:117]
	v_mfma_i32_16x16x64_i8 v[114:117], v[158:161], v[192:195], v[114:117]
	v_mfma_i32_16x16x64_i8 v[102:105], v[146:149], v[202:205], v[102:105]
	v_mfma_i32_16x16x64_i8 v[102:105], v[150:153], v[206:209], v[102:105]
	v_mfma_i32_16x16x64_i8 v[98:101], v[154:157], v[202:205], v[98:101]
	v_mfma_i32_16x16x64_i8 v[98:101], v[158:161], v[206:209], v[98:101]
	s_barrier
	s_setprio 2
	v_mfma_i32_16x16x64_i8 v[86:89], v[146:149], v[210:213], v[86:89]
	ds_read_b128 v[188:191], v187 offset:49152
	ds_read_b128 v[192:195], v187 offset:50176
	ds_read_b128 v[202:205], v187 offset:51200
	ds_read_b128 v[206:209], v187 offset:52224
	v_mfma_i32_16x16x64_i8 v[86:89], v[150:153], v[214:217], v[86:89]
	v_mfma_i32_16x16x64_i8 v[82:85], v[154:157], v[210:213], v[82:85]
	v_mfma_i32_16x16x64_i8 v[82:85], v[158:161], v[214:217], v[82:85]
	v_mfma_i32_16x16x64_i8 v[70:73], v[146:149], v[220:223], v[70:73]
	ds_read_b128 v[210:213], v187 offset:53248
	v_mfma_i32_16x16x64_i8 v[70:73], v[150:153], v[224:227], v[70:73]
	ds_read_b128 v[214:217], v187 offset:54272
	v_mfma_i32_16x16x64_i8 v[66:69], v[154:157], v[220:223], v[66:69]
	v_mfma_i32_16x16x64_i8 v[66:69], v[158:161], v[224:227], v[66:69]
	s_setprio 0
	s_add_i32 s34, s56, s9
	v_lshl_add_u64 v[174:175], v[174:175], 0, s[4:5]
	s_mov_b32 m0, s34
	ds_read_b128 v[220:223], v187 offset:55296
	ds_read_b128 v[224:227], v187 offset:56320
	global_load_lds_dwordx4 v[174:175], off
	s_add_i32 m0, s34, 0x2000
	s_add_u32 s30, s30, 0x80080
	v_lshl_add_u64 v[174:175], v[176:177], 0, s[4:5]
	s_addc_u32 s31, s31, 0
	s_add_i32 s34, s57, s9
	global_load_lds_dwordx4 v[174:175], off
	v_lshl_add_u64 v[174:175], s[30:31], 0, v[166:167]
	s_mov_b32 m0, s34
	s_nop 0
	global_load_lds_dwordx4 v[174:175], off
	v_lshl_add_u64 v[174:175], s[30:31], 0, v[162:163]
	s_add_i32 m0, s34, 0x2000
	s_nop 0
	global_load_lds_dwordx4 v[174:175], off
	v_lshl_add_u64 v[174:175], v[178:179], 0, s[4:5]
	s_mov_b32 m0, s39
	s_nop 0
	global_load_lds_dwordx4 v[174:175], off
	v_lshl_add_u64 v[174:175], v[180:181], 0, s[4:5]
	s_mov_b32 m0, s40
	s_nop 0
	global_load_lds_dwordx4 v[174:175], off
	s_waitcnt vmcnt(8)
	s_waitcnt lgkmcnt(0)
	s_barrier
	s_setprio 1
	s_waitcnt lgkmcnt(0)
	v_mfma_i32_16x16x64_i8 v[62:65], v[130:133], v[188:191], v[62:65]
	v_mfma_i32_16x16x64_i8 v[62:65], v[134:137], v[192:195], v[62:65]
	v_mfma_i32_16x16x64_i8 v[58:61], v[138:141], v[188:191], v[58:61]
	v_mfma_i32_16x16x64_i8 v[58:61], v[142:145], v[192:195], v[58:61]
	v_mfma_i32_16x16x64_i8 v[46:49], v[130:133], v[202:205], v[46:49]
	v_mfma_i32_16x16x64_i8 v[46:49], v[134:137], v[206:209], v[46:49]
	v_mfma_i32_16x16x64_i8 v[42:45], v[138:141], v[202:205], v[42:45]
	v_mfma_i32_16x16x64_i8 v[42:45], v[142:145], v[206:209], v[42:45]
	v_mfma_i32_16x16x64_i8 v[30:33], v[130:133], v[210:213], v[30:33]
	v_mfma_i32_16x16x64_i8 v[30:33], v[134:137], v[214:217], v[30:33]
	v_mfma_i32_16x16x64_i8 v[26:29], v[138:141], v[210:213], v[26:29]
	v_mfma_i32_16x16x64_i8 v[26:29], v[142:145], v[214:217], v[26:29]
	v_mfma_i32_16x16x64_i8 v[14:17], v[130:133], v[220:223], v[14:17]
	v_mfma_i32_16x16x64_i8 v[14:17], v[134:137], v[224:227], v[14:17]
	v_mfma_i32_16x16x64_i8 v[10:13], v[138:141], v[220:223], v[10:13]
	v_mfma_i32_16x16x64_i8 v[10:13], v[142:145], v[224:227], v[10:13]
	v_mfma_i32_16x16x64_i8 v[54:57], v[146:149], v[188:191], v[54:57]
	v_mfma_i32_16x16x64_i8 v[54:57], v[150:153], v[192:195], v[54:57]
	v_mfma_i32_16x16x64_i8 v[50:53], v[154:157], v[188:191], v[50:53]
	v_mfma_i32_16x16x64_i8 v[50:53], v[158:161], v[192:195], v[50:53]
	v_mfma_i32_16x16x64_i8 v[38:41], v[146:149], v[202:205], v[38:41]
	v_mfma_i32_16x16x64_i8 v[38:41], v[150:153], v[206:209], v[38:41]
	v_mfma_i32_16x16x64_i8 v[34:37], v[154:157], v[202:205], v[34:37]
	v_mfma_i32_16x16x64_i8 v[34:37], v[158:161], v[206:209], v[34:37]
	v_mfma_i32_16x16x64_i8 v[22:25], v[146:149], v[210:213], v[22:25]
	v_mfma_i32_16x16x64_i8 v[22:25], v[150:153], v[214:217], v[22:25]
	v_mfma_i32_16x16x64_i8 v[18:21], v[154:157], v[210:213], v[18:21]
	v_mfma_i32_16x16x64_i8 v[18:21], v[158:161], v[214:217], v[18:21]
	s_barrier
	s_setprio 2
	v_mfma_i32_16x16x64_i8 v[6:9], v[146:149], v[220:223], v[6:9]
	v_mfma_i32_16x16x64_i8 v[6:9], v[150:153], v[224:227], v[6:9]
	v_mfma_i32_16x16x64_i8 v[2:5], v[154:157], v[220:223], v[2:5]
	v_mfma_i32_16x16x64_i8 v[2:5], v[158:161], v[224:227], v[2:5]
	s_setprio 0
	s_add_i32 s45, s45, 2
	s_add_u32 s28, s28, 0x100
	s_addc_u32 s29, s29, 0
	s_add_u32 s43, s43, 0x100
	s_addc_u32 s44, s44, 0
	s_cmp_gt_u32 s45, 29
	s_cbranch_scc0 .LBB0_961
	s_nop 15
	s_nop 15
	s_and_b64 vcc, exec, s[6:7]
	s_cbranch_vccz .LBB0_964
	s_barrier

.LBB0_1058:
	ds_read_b128 v[128:131], v194
	ds_read_b128 v[132:135], v194 offset:1024
	ds_read_b128 v[136:139], v194 offset:2048
	ds_read_b128 v[140:143], v194 offset:3072
	ds_read_b128 v[144:147], v195
	ds_read_b128 v[148:151], v195 offset:1024
	ds_read_b128 v[152:155], v195 offset:2048
	ds_read_b128 v[156:159], v195 offset:3072
	s_add_u32 s2, s0, 0x100
	s_addc_u32 s3, s1, 0
	s_cmpk_eq_i32 s39, 0xa8
	s_cselect_b32 s37, s31, s3
	s_cselect_b32 s36, s30, s2
	s_cselect_b32 s5, s7, s38
	s_cselect_b32 s4, s6, s29
	v_lshl_add_u64 v[188:189], s[0:1], 0, v[168:169]
	s_add_i32 m0, s27, 0xc000
	ds_read_b128 v[172:175], v196
	ds_read_b128 v[176:179], v196 offset:1024
	ds_read_b128 v[180:183], v196 offset:2048
	ds_read_b128 v[184:187], v196 offset:3072
	ds_read_b128 v[200:203], v196 offset:4096
	ds_read_b128 v[204:207], v196 offset:5120
	ds_read_b128 v[208:211], v196 offset:6144
	ds_read_b128 v[212:215], v196 offset:7168
	global_load_lds_dwordx4 v[188:189], off
	v_lshl_add_u64 v[188:189], s[0:1], 0, v[170:171]
	s_add_i32 m0, s27, 0xe000
	s_nop 0
	global_load_lds_dwordx4 v[188:189], off
	s_waitcnt vmcnt(8)
	s_waitcnt lgkmcnt(0)
	s_barrier
	s_setprio 1
	s_waitcnt lgkmcnt(0)
	v_mfma_f32_16x16x32_bf16 v[12:15], v[128:131], v[172:175], v[12:15]
	v_mfma_f32_16x16x32_bf16 v[8:11], v[136:139], v[172:175], v[8:11]
	v_mfma_f32_16x16x32_bf16 v[36:39], v[128:131], v[180:183], v[36:39]
	v_mfma_f32_16x16x32_bf16 v[32:35], v[136:139], v[180:183], v[32:35]
	v_mfma_f32_16x16x32_bf16 v[44:47], v[128:131], v[200:203], v[44:47]
	v_mfma_f32_16x16x32_bf16 v[40:43], v[136:139], v[200:203], v[40:43]
	v_mfma_f32_16x16x32_bf16 v[64:67], v[128:131], v[208:211], v[64:67]
	v_mfma_f32_16x16x32_bf16 v[56:59], v[136:139], v[208:211], v[56:59]
	v_mfma_f32_16x16x32_bf16 v[12:15], v[132:135], v[176:179], v[12:15]
	v_mfma_f32_16x16x32_bf16 v[8:11], v[140:143], v[176:179], v[8:11]
	v_mfma_f32_16x16x32_bf16 v[36:39], v[132:135], v[184:187], v[36:39]
	v_mfma_f32_16x16x32_bf16 v[32:35], v[140:143], v[184:187], v[32:35]
	v_mfma_f32_16x16x32_bf16 v[44:47], v[132:135], v[204:207], v[44:47]
	v_mfma_f32_16x16x32_bf16 v[40:43], v[140:143], v[204:207], v[40:43]
	v_mfma_f32_16x16x32_bf16 v[64:67], v[132:135], v[212:215], v[64:67]
	v_mfma_f32_16x16x32_bf16 v[56:59], v[140:143], v[212:215], v[56:59]
	v_mfma_f32_16x16x32_bf16 v[4:7], v[144:147], v[172:175], v[4:7]
	v_mfma_f32_16x16x32_bf16 v[0:3], v[152:155], v[172:175], v[0:3]
	v_mfma_f32_16x16x32_bf16 v[24:27], v[144:147], v[180:183], v[24:27]
	v_mfma_f32_16x16x32_bf16 v[16:19], v[152:155], v[180:183], v[16:19]
	v_mfma_f32_16x16x32_bf16 v[28:31], v[144:147], v[200:203], v[28:31]
	v_mfma_f32_16x16x32_bf16 v[20:23], v[152:155], v[200:203], v[20:23]
	v_mfma_f32_16x16x32_bf16 v[52:55], v[144:147], v[208:211], v[52:55]
	v_mfma_f32_16x16x32_bf16 v[48:51], v[152:155], v[208:211], v[48:51]
	s_barrier
	s_setprio 2
	v_mfma_f32_16x16x32_bf16 v[4:7], v[148:151], v[176:179], v[4:7]
	ds_read_b128 v[172:175], v196 offset:16384
	v_mfma_f32_16x16x32_bf16 v[0:3], v[156:159], v[176:179], v[0:3]
	v_mfma_f32_16x16x32_bf16 v[24:27], v[148:151], v[184:187], v[24:27]
	v_mfma_f32_16x16x32_bf16 v[16:19], v[156:159], v[184:187], v[16:19]
	ds_read_b128 v[176:179], v196 offset:17408
	ds_read_b128 v[180:183], v196 offset:18432
	v_mfma_f32_16x16x32_bf16 v[28:31], v[148:151], v[204:207], v[28:31]
	v_mfma_f32_16x16x32_bf16 v[20:23], v[156:159], v[204:207], v[20:23]
	ds_read_b128 v[184:187], v196 offset:19456
	ds_read_b128 v[200:203], v196 offset:20480
	v_mfma_f32_16x16x32_bf16 v[52:55], v[148:151], v[212:215], v[52:55]
	v_mfma_f32_16x16x32_bf16 v[48:51], v[156:159], v[212:215], v[48:51]
	ds_read_b128 v[204:207], v196 offset:21504
	ds_read_b128 v[208:211], v196 offset:22528
	s_setprio 0
	s_add_i32 s0, s17, s25
	v_lshl_add_u64 v[188:189], s[4:5], 0, v[162:163]
	s_mov_b32 m0, s0
	ds_read_b128 v[212:215], v196 offset:23552
	global_load_lds_dwordx4 v[188:189], off
	s_add_i32 m0, s0, 0x2000
	s_add_u32 s0, s4, 0x2b0000
	v_lshl_add_u64 v[216:217], s[4:5], 0, v[166:167]
	s_addc_u32 s1, s5, 0
	s_add_i32 s40, s55, s25
	global_load_lds_dwordx4 v[216:217], off
	v_lshl_add_u64 v[220:221], s[0:1], 0, v[162:163]
	s_mov_b32 m0, s40
	v_lshl_add_u64 v[222:223], s[36:37], 0, v[164:165]
	global_load_lds_dwordx4 v[220:221], off
	v_lshl_add_u64 v[220:221], s[0:1], 0, v[166:167]
	s_add_i32 m0, s40, 0x2000
	s_nop 0
	global_load_lds_dwordx4 v[220:221], off
	v_lshl_add_u64 v[220:221], s[36:37], 0, v[160:161]
	s_mov_b32 m0, s27
	s_nop 0
	global_load_lds_dwordx4 v[220:221], off
	s_mov_b32 m0, s33
	s_nop 0
	global_load_lds_dwordx4 v[222:223], off
	s_waitcnt vmcnt(8)
	s_waitcnt lgkmcnt(0)
	s_barrier
	s_setprio 1
	s_waitcnt lgkmcnt(0)
	v_mfma_f32_16x16x32_bf16 v[76:79], v[128:131], v[172:175], v[76:79]
	v_mfma_f32_16x16x32_bf16 v[72:75], v[136:139], v[172:175], v[72:75]
	v_mfma_f32_16x16x32_bf16 v[92:95], v[128:131], v[180:183], v[92:95]
	v_mfma_f32_16x16x32_bf16 v[88:91], v[136:139], v[180:183], v[88:91]
	v_mfma_f32_16x16x32_bf16 v[108:111], v[128:131], v[200:203], v[108:111]
	v_mfma_f32_16x16x32_bf16 v[104:107], v[136:139], v[200:203], v[104:107]
	v_mfma_f32_16x16x32_bf16 v[124:127], v[128:131], v[208:211], v[124:127]
	v_mfma_f32_16x16x32_bf16 v[120:123], v[136:139], v[208:211], v[120:123]
	v_mfma_f32_16x16x32_bf16 v[76:79], v[132:135], v[176:179], v[76:79]
	v_mfma_f32_16x16x32_bf16 v[72:75], v[140:143], v[176:179], v[72:75]
	v_mfma_f32_16x16x32_bf16 v[92:95], v[132:135], v[184:187], v[92:95]
	v_mfma_f32_16x16x32_bf16 v[88:91], v[140:143], v[184:187], v[88:91]
	v_mfma_f32_16x16x32_bf16 v[108:111], v[132:135], v[204:207], v[108:111]
	v_mfma_f32_16x16x32_bf16 v[104:107], v[140:143], v[204:207], v[104:107]
	v_mfma_f32_16x16x32_bf16 v[124:127], v[132:135], v[212:215], v[124:127]
	v_mfma_f32_16x16x32_bf16 v[120:123], v[140:143], v[212:215], v[120:123]
	v_mfma_f32_16x16x32_bf16 v[68:71], v[144:147], v[172:175], v[68:71]
	v_mfma_f32_16x16x32_bf16 v[60:63], v[152:155], v[172:175], v[60:63]
	v_mfma_f32_16x16x32_bf16 v[84:87], v[144:147], v[180:183], v[84:87]
	v_mfma_f32_16x16x32_bf16 v[80:83], v[152:155], v[180:183], v[80:83]
	v_mfma_f32_16x16x32_bf16 v[100:103], v[144:147], v[200:203], v[100:103]
	v_mfma_f32_16x16x32_bf16 v[96:99], v[152:155], v[200:203], v[96:99]
	v_mfma_f32_16x16x32_bf16 v[116:119], v[144:147], v[208:211], v[116:119]
	v_mfma_f32_16x16x32_bf16 v[112:115], v[152:155], v[208:211], v[112:115]
	s_barrier
	s_setprio 2
	v_mfma_f32_16x16x32_bf16 v[68:71], v[148:151], v[176:179], v[68:71]
	v_add_u32_e32 v140, s56, v193
	ds_read_b128 v[128:131], v140
	ds_read_b128 v[132:135], v140 offset:1024
	ds_read_b128 v[136:139], v140 offset:2048
	ds_read_b128 v[140:143], v140 offset:3072
	v_mfma_f32_16x16x32_bf16 v[60:63], v[156:159], v[176:179], v[60:63]
	v_mfma_f32_16x16x32_bf16 v[84:87], v[148:151], v[184:187], v[84:87]
	v_mfma_f32_16x16x32_bf16 v[80:83], v[156:159], v[184:187], v[80:83]
	v_mfma_f32_16x16x32_bf16 v[100:103], v[148:151], v[204:207], v[100:103]
	v_mfma_f32_16x16x32_bf16 v[96:99], v[156:159], v[204:207], v[96:99]
	v_mfma_f32_16x16x32_bf16 v[116:119], v[148:151], v[212:215], v[116:119]
	v_mfma_f32_16x16x32_bf16 v[112:115], v[156:159], v[212:215], v[112:115]
	s_setprio 0
	v_add_u32_e32 v156, s57, v193
	ds_read_b128 v[144:147], v156
	ds_read_b128 v[148:151], v156 offset:1024
	ds_read_b128 v[152:155], v156 offset:2048
	ds_read_b128 v[156:159], v156 offset:3072
	s_add_u32 s0, s36, 0x2b0000
	s_addc_u32 s1, s37, 0
	s_mov_b32 m0, s46
	v_lshl_add_u64 v[224:225], s[0:1], 0, v[160:161]
	ds_read_b128 v[172:175], v196 offset:32768
	ds_read_b128 v[176:179], v196 offset:33792
	ds_read_b128 v[180:183], v196 offset:34816
	ds_read_b128 v[184:187], v196 offset:35840
	ds_read_b128 v[200:203], v196 offset:36864
	ds_read_b128 v[204:207], v196 offset:37888
	ds_read_b128 v[208:211], v196 offset:38912
	ds_read_b128 v[212:215], v196 offset:39936
	global_load_lds_dwordx4 v[224:225], off
	v_lshl_add_u64 v[224:225], s[0:1], 0, v[164:165]
	s_mov_b32 m0, s47
	s_nop 0
	global_load_lds_dwordx4 v[224:225], off
	s_waitcnt vmcnt(8)
	s_waitcnt lgkmcnt(0)
	s_barrier
	s_setprio 1
	s_waitcnt lgkmcnt(0)
	v_mfma_f32_16x16x32_bf16 v[12:15], v[128:131], v[172:175], v[12:15]
	v_mfma_f32_16x16x32_bf16 v[8:11], v[136:139], v[172:175], v[8:11]
	v_mfma_f32_16x16x32_bf16 v[36:39], v[128:131], v[180:183], v[36:39]
	v_mfma_f32_16x16x32_bf16 v[32:35], v[136:139], v[180:183], v[32:35]
	v_mfma_f32_16x16x32_bf16 v[44:47], v[128:131], v[200:203], v[44:47]
	v_mfma_f32_16x16x32_bf16 v[40:43], v[136:139], v[200:203], v[40:43]
	v_mfma_f32_16x16x32_bf16 v[64:67], v[128:131], v[208:211], v[64:67]
	v_mfma_f32_16x16x32_bf16 v[56:59], v[136:139], v[208:211], v[56:59]
	v_mfma_f32_16x16x32_bf16 v[12:15], v[132:135], v[176:179], v[12:15]
	v_mfma_f32_16x16x32_bf16 v[8:11], v[140:143], v[176:179], v[8:11]
	v_mfma_f32_16x16x32_bf16 v[36:39], v[132:135], v[184:187], v[36:39]
	v_mfma_f32_16x16x32_bf16 v[32:35], v[140:143], v[184:187], v[32:35]
	v_mfma_f32_16x16x32_bf16 v[44:47], v[132:135], v[204:207], v[44:47]
	v_mfma_f32_16x16x32_bf16 v[40:43], v[140:143], v[204:207], v[40:43]
	v_mfma_f32_16x16x32_bf16 v[64:67], v[132:135], v[212:215], v[64:67]
	v_mfma_f32_16x16x32_bf16 v[56:59], v[140:143], v[212:215], v[56:59]
	v_mfma_f32_16x16x32_bf16 v[4:7], v[144:147], v[172:175], v[4:7]
	v_mfma_f32_16x16x32_bf16 v[0:3], v[152:155], v[172:175], v[0:3]
	v_mfma_f32_16x16x32_bf16 v[24:27], v[144:147], v[180:183], v[24:27]
	v_mfma_f32_16x16x32_bf16 v[16:19], v[152:155], v[180:183], v[16:19]
	v_mfma_f32_16x16x32_bf16 v[28:31], v[144:147], v[200:203], v[28:31]
	v_mfma_f32_16x16x32_bf16 v[20:23], v[152:155], v[200:203], v[20:23]
	v_mfma_f32_16x16x32_bf16 v[52:55], v[144:147], v[208:211], v[52:55]
	v_mfma_f32_16x16x32_bf16 v[48:51], v[152:155], v[208:211], v[48:51]
	s_barrier
	s_setprio 2
	v_mfma_f32_16x16x32_bf16 v[4:7], v[148:151], v[176:179], v[4:7]
	ds_read_b128 v[172:175], v196 offset:49152
	v_mfma_f32_16x16x32_bf16 v[0:3], v[156:159], v[176:179], v[0:3]
	v_mfma_f32_16x16x32_bf16 v[24:27], v[148:151], v[184:187], v[24:27]
	v_mfma_f32_16x16x32_bf16 v[16:19], v[156:159], v[184:187], v[16:19]
	ds_read_b128 v[176:179], v196 offset:50176
	ds_read_b128 v[180:183], v196 offset:51200
	v_mfma_f32_16x16x32_bf16 v[28:31], v[148:151], v[204:207], v[28:31]
	v_mfma_f32_16x16x32_bf16 v[20:23], v[156:159], v[204:207], v[20:23]
	ds_read_b128 v[184:187], v196 offset:52224
	ds_read_b128 v[200:203], v196 offset:53248
	v_mfma_f32_16x16x32_bf16 v[52:55], v[148:151], v[212:215], v[52:55]
	v_mfma_f32_16x16x32_bf16 v[48:51], v[156:159], v[212:215], v[48:51]
	ds_read_b128 v[204:207], v196 offset:54272
	ds_read_b128 v[208:211], v196 offset:55296
	s_setprio 0
	s_add_i32 s0, s56, s25
	v_lshl_add_u64 v[188:189], v[188:189], 0, s[18:19]
	s_mov_b32 m0, s0
	ds_read_b128 v[212:215], v196 offset:56320
	global_load_lds_dwordx4 v[188:189], off
	s_add_i32 m0, s0, 0x2000
	s_add_u32 s0, s4, 0x2b0080
	v_lshl_add_u64 v[188:189], v[216:217], 0, s[18:19]
	s_addc_u32 s1, s5, 0
	s_add_i32 s4, s57, s25
	global_load_lds_dwordx4 v[188:189], off
	v_lshl_add_u64 v[188:189], s[0:1], 0, v[162:163]
	s_mov_b32 m0, s4
	s_nop 0
	global_load_lds_dwordx4 v[188:189], off
	v_lshl_add_u64 v[188:189], s[0:1], 0, v[166:167]
	s_add_i32 m0, s4, 0x2000
	s_nop 0
	global_load_lds_dwordx4 v[188:189], off
	v_lshl_add_u64 v[188:189], v[220:221], 0, s[18:19]
	s_mov_b32 m0, s52
	s_nop 0
	global_load_lds_dwordx4 v[188:189], off
	v_lshl_add_u64 v[188:189], v[222:223], 0, s[18:19]
	s_mov_b32 m0, s53
	s_nop 0
	global_load_lds_dwordx4 v[188:189], off
	s_waitcnt vmcnt(8)
	s_waitcnt lgkmcnt(0)
	s_barrier
	s_setprio 1
	s_waitcnt lgkmcnt(0)
	v_mfma_f32_16x16x32_bf16 v[76:79], v[128:131], v[172:175], v[76:79]
	v_mfma_f32_16x16x32_bf16 v[72:75], v[136:139], v[172:175], v[72:75]
	v_mfma_f32_16x16x32_bf16 v[92:95], v[128:131], v[180:183], v[92:95]
	v_mfma_f32_16x16x32_bf16 v[88:91], v[136:139], v[180:183], v[88:91]
	v_mfma_f32_16x16x32_bf16 v[108:111], v[128:131], v[200:203], v[108:111]
	v_mfma_f32_16x16x32_bf16 v[104:107], v[136:139], v[200:203], v[104:107]
	v_mfma_f32_16x16x32_bf16 v[124:127], v[128:131], v[208:211], v[124:127]
	v_mfma_f32_16x16x32_bf16 v[120:123], v[136:139], v[208:211], v[120:123]
	v_mfma_f32_16x16x32_bf16 v[76:79], v[132:135], v[176:179], v[76:79]
	v_mfma_f32_16x16x32_bf16 v[72:75], v[140:143], v[176:179], v[72:75]
	v_mfma_f32_16x16x32_bf16 v[92:95], v[132:135], v[184:187], v[92:95]
	v_mfma_f32_16x16x32_bf16 v[88:91], v[140:143], v[184:187], v[88:91]
	v_mfma_f32_16x16x32_bf16 v[108:111], v[132:135], v[204:207], v[108:111]
	v_mfma_f32_16x16x32_bf16 v[104:107], v[140:143], v[204:207], v[104:107]
	v_mfma_f32_16x16x32_bf16 v[124:127], v[132:135], v[212:215], v[124:127]
	v_mfma_f32_16x16x32_bf16 v[120:123], v[140:143], v[212:215], v[120:123]
	v_mfma_f32_16x16x32_bf16 v[68:71], v[144:147], v[172:175], v[68:71]
	v_mfma_f32_16x16x32_bf16 v[60:63], v[152:155], v[172:175], v[60:63]
	v_mfma_f32_16x16x32_bf16 v[84:87], v[144:147], v[180:183], v[84:87]
	v_mfma_f32_16x16x32_bf16 v[80:83], v[152:155], v[180:183], v[80:83]
	v_mfma_f32_16x16x32_bf16 v[100:103], v[144:147], v[200:203], v[100:103]
	v_mfma_f32_16x16x32_bf16 v[96:99], v[152:155], v[200:203], v[96:99]
	v_mfma_f32_16x16x32_bf16 v[116:119], v[144:147], v[208:211], v[116:119]
	v_mfma_f32_16x16x32_bf16 v[112:115], v[152:155], v[208:211], v[112:115]
	v_mfma_f32_16x16x32_bf16 v[68:71], v[148:151], v[176:179], v[68:71]
	v_mfma_f32_16x16x32_bf16 v[60:63], v[156:159], v[176:179], v[60:63]
	v_mfma_f32_16x16x32_bf16 v[84:87], v[148:151], v[184:187], v[84:87]
	v_mfma_f32_16x16x32_bf16 v[80:83], v[156:159], v[184:187], v[80:83]
	s_barrier
	s_setprio 2
	v_mfma_f32_16x16x32_bf16 v[100:103], v[148:151], v[204:207], v[100:103]
	v_mfma_f32_16x16x32_bf16 v[96:99], v[156:159], v[204:207], v[96:99]
	v_mfma_f32_16x16x32_bf16 v[116:119], v[148:151], v[212:215], v[116:119]
	v_mfma_f32_16x16x32_bf16 v[112:115], v[156:159], v[212:215], v[112:115]
	s_setprio 0
	s_add_i32 s39, s39, 2
	s_add_u32 s29, s29, 0x100
	s_addc_u32 s38, s38, 0
	s_cmpk_gt_u32 s39, 0xa9
	s_mov_b64 s[0:1], s[2:3]
	s_cbranch_scc0 .LBB0_1058
	s_and_b64 vcc, exec, s[20:21]
	s_cbranch_vccz .LBB0_1061
	s_barrier
